# phase 0 adaLN GEMV: weight-row loads software-pipelined three groups ahead (fully unrolled 16 groups) instead of one group per iteration
# baseline (speedup 1.0000x reference)
; __global__ void __launch_bounds__(512) mega(Params p) {
;     ...
;             for (int it = bx; it < DEPTH * 96; it += G) {
;                 const int i = it / 96, nb = it % 96; const float* Wp = p.in[4] + (size_t)i * 1024 * 6144 + nb * 64 + lane;
;                 float a0 = 0.f, a1 = 0.f, a2 = 0.f, a3 = 0.f, a4 = 0.f;
; #pragma unroll 8
;                 for (int kk = 0; kk < 128; ++kk) { const int k = wave * 128 + kk; const float w = Wp[(size_t)k * 6144];
;                     a0 += sv[k] * w; a1 += sv[1024 + k] * w; a2 += sv[2048 + k] * w; a3 += sv[3072 + k] * w; a4 += sv[4096 + k] * w; }
;                 red[(wave * 5 + 0) * 64 + lane] = a0; red[(wave * 5 + 1) * 64 + lane] = a1; red[(wave * 5 + 2) * 64 + lane] = a2; red[(wave * 5 + 3) * 64 + lane] = a3; red[(wave * 5 + 4) * 64 + lane] = a4;
.LBB0_631:
	v_lshl_add_u64 v[16:17], v[4:5], 0, s[8:9]
	v_add_co_u32_e64 v18, s[4:5], s77, v16
	global_load_dword v56, v[16:17], off
	s_nop 0
	v_addc_co_u32_e64 v19, s[4:5], 0, v17, s[4:5]
	v_add_co_u32_e64 v20, s[4:5], s87, v16
	s_nop 0
	v_addc_co_u32_e64 v21, s[4:5], 0, v17, s[4:5]
	v_add_co_u32_e64 v22, s[4:5], s76, v16
	s_add_u32 s8, s8, 0x30000
	s_nop 0
	v_addc_co_u32_e64 v23, s[4:5], 0, v17, s[4:5]
	s_mov_b32 s4, 0x18000
	s_nop 0
	v_add_co_u32_e64 v24, s[4:5], s4, v16
	s_addc_u32 s9, s9, 0
	s_nop 0
	v_addc_co_u32_e64 v25, s[4:5], 0, v17, s[4:5]
	s_mov_b32 s4, 0x1e000
	s_nop 0
	v_add_co_u32_e64 v26, s[4:5], s4, v16
	s_nop 0
	v_addc_co_u32_e64 v27, s[4:5], 0, v17, s[4:5]
	s_mov_b32 s4, 0x24000
	s_nop 0
	v_add_co_u32_e64 v28, s[4:5], s4, v16
	s_nop 0
	v_addc_co_u32_e64 v29, s[4:5], 0, v17, s[4:5]
	s_mov_b32 s4, 0x2a000
	s_nop 0
	v_add_co_u32_e64 v16, s[4:5], s4, v16
	s_nop 1
	v_addc_co_u32_e64 v17, s[4:5], 0, v17, s[4:5]
	global_load_dword v58, v[18:19], off
	global_load_dword v60, v[20:21], off
	global_load_dword v62, v[22:23], off
	global_load_dword v64, v[24:25], off
	global_load_dword v66, v[26:27], off
	global_load_dword v68, v[28:29], off
	global_load_dword v70, v[16:17], off
	v_lshl_add_u64 v[16:17], v[4:5], 0, s[8:9]
	v_add_co_u32_e64 v18, s[4:5], s77, v16
	global_load_dword v74, v[16:17], off
	s_nop 0
	v_addc_co_u32_e64 v19, s[4:5], 0, v17, s[4:5]
	v_add_co_u32_e64 v20, s[4:5], s87, v16
	s_nop 0
	v_addc_co_u32_e64 v21, s[4:5], 0, v17, s[4:5]
	v_add_co_u32_e64 v22, s[4:5], s76, v16
	s_add_u32 s8, s8, 0x30000
	s_nop 0
	v_addc_co_u32_e64 v23, s[4:5], 0, v17, s[4:5]
	s_mov_b32 s4, 0x18000
	s_nop 0
	v_add_co_u32_e64 v24, s[4:5], s4, v16
	s_addc_u32 s9, s9, 0
	s_nop 0
	v_addc_co_u32_e64 v25, s[4:5], 0, v17, s[4:5]
	s_mov_b32 s4, 0x1e000
	s_nop 0
	v_add_co_u32_e64 v26, s[4:5], s4, v16
	s_nop 0
	v_addc_co_u32_e64 v27, s[4:5], 0, v17, s[4:5]
	s_mov_b32 s4, 0x24000
	s_nop 0
	v_add_co_u32_e64 v28, s[4:5], s4, v16
	s_nop 0
	v_addc_co_u32_e64 v29, s[4:5], 0, v17, s[4:5]
	s_mov_b32 s4, 0x2a000
	s_nop 0
	v_add_co_u32_e64 v16, s[4:5], s4, v16
	s_nop 1
	v_addc_co_u32_e64 v17, s[4:5], 0, v17, s[4:5]
	global_load_dword v76, v[18:19], off
	global_load_dword v78, v[20:21], off
	global_load_dword v80, v[22:23], off
	global_load_dword v82, v[24:25], off
	global_load_dword v84, v[26:27], off
	global_load_dword v86, v[28:29], off
	global_load_dword v88, v[16:17], off
	v_lshl_add_u64 v[16:17], v[4:5], 0, s[8:9]
	v_add_co_u32_e64 v18, s[4:5], s77, v16
	global_load_dword v90, v[16:17], off
	s_nop 0
	v_addc_co_u32_e64 v19, s[4:5], 0, v17, s[4:5]
	v_add_co_u32_e64 v20, s[4:5], s87, v16
	s_nop 0
	v_addc_co_u32_e64 v21, s[4:5], 0, v17, s[4:5]
	v_add_co_u32_e64 v22, s[4:5], s76, v16
	s_add_u32 s8, s8, 0x30000
	s_nop 0
	v_addc_co_u32_e64 v23, s[4:5], 0, v17, s[4:5]
	s_mov_b32 s4, 0x18000
	s_nop 0
	v_add_co_u32_e64 v24, s[4:5], s4, v16
	s_addc_u32 s9, s9, 0
	s_nop 0
	v_addc_co_u32_e64 v25, s[4:5], 0, v17, s[4:5]
	s_mov_b32 s4, 0x1e000
	s_nop 0
	v_add_co_u32_e64 v26, s[4:5], s4, v16
	s_nop 0
	v_addc_co_u32_e64 v27, s[4:5], 0, v17, s[4:5]
	s_mov_b32 s4, 0x24000
	s_nop 0
	v_add_co_u32_e64 v28, s[4:5], s4, v16
	s_nop 0
	v_addc_co_u32_e64 v29, s[4:5], 0, v17, s[4:5]
	s_mov_b32 s4, 0x2a000
	s_nop 0
	v_add_co_u32_e64 v16, s[4:5], s4, v16
	s_nop 1
	v_addc_co_u32_e64 v17, s[4:5], 0, v17, s[4:5]
	global_load_dword v92, v[18:19], off
	global_load_dword v94, v[20:21], off
	global_load_dword v96, v[22:23], off
	global_load_dword v98, v[24:25], off
	global_load_dword v100, v[26:27], off
	global_load_dword v102, v[28:29], off
	global_load_dword v104, v[16:17], off
	v_lshl_add_u64 v[16:17], v[4:5], 0, s[8:9]
	v_add_co_u32_e64 v18, s[4:5], s77, v16
	global_load_dword v106, v[16:17], off
	s_nop 0
	v_addc_co_u32_e64 v19, s[4:5], 0, v17, s[4:5]
	v_add_co_u32_e64 v20, s[4:5], s87, v16
	s_nop 0
	v_addc_co_u32_e64 v21, s[4:5], 0, v17, s[4:5]
	v_add_co_u32_e64 v22, s[4:5], s76, v16
	s_add_u32 s8, s8, 0x30000
	s_nop 0
	v_addc_co_u32_e64 v23, s[4:5], 0, v17, s[4:5]
	s_mov_b32 s4, 0x18000
	s_nop 0
	v_add_co_u32_e64 v24, s[4:5], s4, v16
	s_addc_u32 s9, s9, 0
	s_nop 0
	v_addc_co_u32_e64 v25, s[4:5], 0, v17, s[4:5]
	s_mov_b32 s4, 0x1e000
	s_nop 0
	v_add_co_u32_e64 v26, s[4:5], s4, v16
	s_nop 0
	v_addc_co_u32_e64 v27, s[4:5], 0, v17, s[4:5]
	s_mov_b32 s4, 0x24000
	s_nop 0
	v_add_co_u32_e64 v28, s[4:5], s4, v16
	s_nop 0
	v_addc_co_u32_e64 v29, s[4:5], 0, v17, s[4:5]
	s_mov_b32 s4, 0x2a000
	s_nop 0
	v_add_co_u32_e64 v16, s[4:5], s4, v16
	s_nop 1
	v_addc_co_u32_e64 v17, s[4:5], 0, v17, s[4:5]
	global_load_dword v108, v[18:19], off
	global_load_dword v110, v[20:21], off
	global_load_dword v112, v[22:23], off
	global_load_dword v114, v[24:25], off
	global_load_dword v116, v[26:27], off
	global_load_dword v118, v[28:29], off
	global_load_dword v120, v[16:17], off
	v_mov_b32_e32 v15, s10
	ds_read_b128 v[16:19], v15
	ds_read_b128 v[20:23], v15 offset:16
	ds_read_b128 v[24:27], v15 offset:4096
	ds_read_b128 v[28:31], v15 offset:4112
	ds_read_b128 v[32:35], v15 offset:8192
	ds_read_b128 v[36:39], v15 offset:8208
	ds_read_b128 v[40:43], v15 offset:12288
	ds_read_b128 v[44:47], v15 offset:12304
	ds_read_b128 v[48:51], v15 offset:16384
	ds_read_b128 v[52:55], v15 offset:16400
	s_waitcnt lgkmcnt(9)
	v_mov_b32_e32 v72, v16
	s_waitcnt lgkmcnt(7)
	v_mov_b32_e32 v73, v24
	v_mov_b32_e32 v24, v17
	v_mov_b32_e32 v16, v18
	v_mov_b32_e32 v17, v26
	v_mov_b32_e32 v26, v19
	s_waitcnt lgkmcnt(5)
	v_mov_b32_e32 v18, v32
	s_waitcnt lgkmcnt(3)
	v_mov_b32_e32 v19, v40
	v_mov_b32_e32 v40, v33
	v_mov_b32_e32 v32, v34
	v_mov_b32_e32 v33, v42
	v_mov_b32_e32 v42, v35
	v_mov_b32_e32 v34, v20
	v_mov_b32_e32 v35, v28
	v_mov_b32_e32 v28, v21
	v_mov_b32_e32 v20, v22
	v_mov_b32_e32 v21, v30
	v_mov_b32_e32 v30, v23
	v_mov_b32_e32 v22, v36
	s_waitcnt lgkmcnt(2)
; __global__ void __launch_bounds__(512) mega(Params p) {
;     ...
;             for (int it = bx; it < DEPTH * 96; it += G) {
;                 const int i = it / 96, nb = it % 96; const float* Wp = p.in[4] + (size_t)i * 1024 * 6144 + nb * 64 + lane;
;                 float a0 = 0.f, a1 = 0.f, a2 = 0.f, a3 = 0.f, a4 = 0.f;
; #pragma unroll 8
;                 for (int kk = 0; kk < 128; ++kk) { const int k = wave * 128 + kk; const float w = Wp[(size_t)k * 6144];
;                     a0 += sv[k] * w; a1 += sv[1024 + k] * w; a2 += sv[2048 + k] * w; a3 += sv[3072 + k] * w; a4 += sv[4096 + k] * w; }
;                 red[(wave * 5 + 0) * 64 + lane] = a0; red[(wave * 5 + 1) * 64 + lane] = a1; red[(wave * 5 + 2) * 64 + lane] = a2; red[(wave * 5 + 3) * 64 + lane] = a3; red[(wave * 5 + 4) * 64 + lane] = a4;
	v_mov_b32_e32 v23, v44
	v_mov_b32_e32 v44, v37
	v_mov_b32_e32 v36, v38
	v_mov_b32_e32 v37, v46
	v_mov_b32_e32 v46, v39
	s_waitcnt vmcnt(31)
	v_pk_fma_f32 v[6:7], v[56:57], v[72:73], v[6:7] op_sel_hi:[0,1,1]
	v_pk_fma_f32 v[12:13], v[56:57], v[18:19], v[12:13] op_sel_hi:[0,1,1]
	s_waitcnt lgkmcnt(1)
	v_fmac_f32_e32 v14, v56, v48
	s_waitcnt vmcnt(30)
	v_pk_fma_f32 v[6:7], v[58:59], v[24:25], v[6:7] op_sel_hi:[0,1,1]
	v_pk_fma_f32 v[12:13], v[58:59], v[40:41], v[12:13] op_sel_hi:[0,1,1]
	v_fmac_f32_e32 v14, v58, v49
	s_waitcnt vmcnt(29)
	v_pk_fma_f32 v[6:7], v[60:61], v[16:17], v[6:7] op_sel_hi:[0,1,1]
	v_pk_fma_f32 v[12:13], v[60:61], v[32:33], v[12:13] op_sel_hi:[0,1,1]
	v_fmac_f32_e32 v14, v60, v50
	s_waitcnt vmcnt(28)
	v_pk_fma_f32 v[6:7], v[62:63], v[26:27], v[6:7] op_sel_hi:[0,1,1]
	v_pk_fma_f32 v[12:13], v[62:63], v[42:43], v[12:13] op_sel_hi:[0,1,1]
	v_fmac_f32_e32 v14, v62, v51
	s_waitcnt vmcnt(27)
	v_pk_fma_f32 v[6:7], v[64:65], v[34:35], v[6:7] op_sel_hi:[0,1,1]
	v_pk_fma_f32 v[12:13], v[64:65], v[22:23], v[12:13] op_sel_hi:[0,1,1]
	s_waitcnt lgkmcnt(0)
	v_fmac_f32_e32 v14, v64, v52
	s_waitcnt vmcnt(26)
	v_pk_fma_f32 v[6:7], v[66:67], v[28:29], v[6:7] op_sel_hi:[0,1,1]
	v_pk_fma_f32 v[12:13], v[66:67], v[44:45], v[12:13] op_sel_hi:[0,1,1]
	v_fmac_f32_e32 v14, v66, v53
	s_waitcnt vmcnt(25)
	v_pk_fma_f32 v[6:7], v[68:69], v[20:21], v[6:7] op_sel_hi:[0,1,1]
	v_pk_fma_f32 v[12:13], v[68:69], v[36:37], v[12:13] op_sel_hi:[0,1,1]
	v_fmac_f32_e32 v14, v68, v54
	s_waitcnt vmcnt(24)
	v_pk_fma_f32 v[6:7], v[70:71], v[30:31], v[6:7] op_sel_hi:[0,1,1]
	v_pk_fma_f32 v[12:13], v[70:71], v[46:47], v[12:13] op_sel_hi:[0,1,1]
	v_fmac_f32_e32 v14, v70, v55
	s_add_i32 s10, s10, 32
	v_lshl_add_u64 v[16:17], v[4:5], 0, s[8:9]
	v_add_co_u32_e64 v18, s[4:5], s77, v16
	global_load_dword v56, v[16:17], off
	s_nop 0
	v_addc_co_u32_e64 v19, s[4:5], 0, v17, s[4:5]
	v_add_co_u32_e64 v20, s[4:5], s87, v16
	s_nop 0
	v_addc_co_u32_e64 v21, s[4:5], 0, v17, s[4:5]
	v_add_co_u32_e64 v22, s[4:5], s76, v16
	s_add_u32 s8, s8, 0x30000
	s_nop 0
	v_addc_co_u32_e64 v23, s[4:5], 0, v17, s[4:5]
	s_mov_b32 s4, 0x18000
	s_nop 0
	v_add_co_u32_e64 v24, s[4:5], s4, v16
	s_addc_u32 s9, s9, 0
	s_nop 0
	v_addc_co_u32_e64 v25, s[4:5], 0, v17, s[4:5]
	s_mov_b32 s4, 0x1e000
	s_nop 0
	v_add_co_u32_e64 v26, s[4:5], s4, v16
	s_nop 0
	v_addc_co_u32_e64 v27, s[4:5], 0, v17, s[4:5]
	s_mov_b32 s4, 0x24000
	s_nop 0
	v_add_co_u32_e64 v28, s[4:5], s4, v16
	s_nop 0
	v_addc_co_u32_e64 v29, s[4:5], 0, v17, s[4:5]
	s_mov_b32 s4, 0x2a000
	s_nop 0
	v_add_co_u32_e64 v16, s[4:5], s4, v16
	s_nop 1
	v_addc_co_u32_e64 v17, s[4:5], 0, v17, s[4:5]
	global_load_dword v58, v[18:19], off
	global_load_dword v60, v[20:21], off
	global_load_dword v62, v[22:23], off
	global_load_dword v64, v[24:25], off
	global_load_dword v66, v[26:27], off
	global_load_dword v68, v[28:29], off
	global_load_dword v70, v[16:17], off
	v_mov_b32_e32 v15, s10
	ds_read_b128 v[16:19], v15
	ds_read_b128 v[20:23], v15 offset:16
	ds_read_b128 v[24:27], v15 offset:4096
	ds_read_b128 v[28:31], v15 offset:4112
	ds_read_b128 v[32:35], v15 offset:8192
	ds_read_b128 v[36:39], v15 offset:8208
	ds_read_b128 v[40:43], v15 offset:12288
	ds_read_b128 v[44:47], v15 offset:12304
	ds_read_b128 v[48:51], v15 offset:16384
	ds_read_b128 v[52:55], v15 offset:16400
	s_waitcnt lgkmcnt(9)
	v_mov_b32_e32 v72, v16
	s_waitcnt lgkmcnt(7)
	v_mov_b32_e32 v73, v24
	v_mov_b32_e32 v24, v17
	v_mov_b32_e32 v16, v18
	v_mov_b32_e32 v17, v26
	v_mov_b32_e32 v26, v19
	s_waitcnt lgkmcnt(5)
	v_mov_b32_e32 v18, v32
	s_waitcnt lgkmcnt(3)
	v_mov_b32_e32 v19, v40
	v_mov_b32_e32 v40, v33
	v_mov_b32_e32 v32, v34
	v_mov_b32_e32 v33, v42
	v_mov_b32_e32 v42, v35
	v_mov_b32_e32 v34, v20
	v_mov_b32_e32 v35, v28
	v_mov_b32_e32 v28, v21
	v_mov_b32_e32 v20, v22
	v_mov_b32_e32 v21, v30
	v_mov_b32_e32 v30, v23
	v_mov_b32_e32 v22, v36
	s_waitcnt lgkmcnt(2)
	v_mov_b32_e32 v23, v44
	v_mov_b32_e32 v44, v37
	v_mov_b32_e32 v36, v38
	v_mov_b32_e32 v37, v46
	v_mov_b32_e32 v46, v39
	s_waitcnt vmcnt(31)
	v_pk_fma_f32 v[6:7], v[74:75], v[72:73], v[6:7] op_sel_hi:[0,1,1]
	v_pk_fma_f32 v[12:13], v[74:75], v[18:19], v[12:13] op_sel_hi:[0,1,1]
	s_waitcnt lgkmcnt(1)
	v_fmac_f32_e32 v14, v74, v48
	s_waitcnt vmcnt(30)
	v_pk_fma_f32 v[6:7], v[76:77], v[24:25], v[6:7] op_sel_hi:[0,1,1]
	v_pk_fma_f32 v[12:13], v[76:77], v[40:41], v[12:13] op_sel_hi:[0,1,1]
	v_fmac_f32_e32 v14, v76, v49
	s_waitcnt vmcnt(29)
	v_pk_fma_f32 v[6:7], v[78:79], v[16:17], v[6:7] op_sel_hi:[0,1,1]
	v_pk_fma_f32 v[12:13], v[78:79], v[32:33], v[12:13] op_sel_hi:[0,1,1]
	v_fmac_f32_e32 v14, v78, v50
	s_waitcnt vmcnt(28)
	v_pk_fma_f32 v[6:7], v[80:81], v[26:27], v[6:7] op_sel_hi:[0,1,1]
	v_pk_fma_f32 v[12:13], v[80:81], v[42:43], v[12:13] op_sel_hi:[0,1,1]
	v_fmac_f32_e32 v14, v80, v51
	s_waitcnt vmcnt(27)
	v_pk_fma_f32 v[6:7], v[82:83], v[34:35], v[6:7] op_sel_hi:[0,1,1]
	v_pk_fma_f32 v[12:13], v[82:83], v[22:23], v[12:13] op_sel_hi:[0,1,1]
	s_waitcnt lgkmcnt(0)
	v_fmac_f32_e32 v14, v82, v52
	s_waitcnt vmcnt(26)
	v_pk_fma_f32 v[6:7], v[84:85], v[28:29], v[6:7] op_sel_hi:[0,1,1]
	v_pk_fma_f32 v[12:13], v[84:85], v[44:45], v[12:13] op_sel_hi:[0,1,1]
	v_fmac_f32_e32 v14, v84, v53
	s_waitcnt vmcnt(25)
	v_pk_fma_f32 v[6:7], v[86:87], v[20:21], v[6:7] op_sel_hi:[0,1,1]
	v_pk_fma_f32 v[12:13], v[86:87], v[36:37], v[12:13] op_sel_hi:[0,1,1]
	v_fmac_f32_e32 v14, v86, v54
	s_waitcnt vmcnt(24)
; __global__ void __launch_bounds__(512) mega(Params p) {
;     ...
;             for (int it = bx; it < DEPTH * 96; it += G) {
;                 const int i = it / 96, nb = it % 96; const float* Wp = p.in[4] + (size_t)i * 1024 * 6144 + nb * 64 + lane;
;                 float a0 = 0.f, a1 = 0.f, a2 = 0.f, a3 = 0.f, a4 = 0.f;
; #pragma unroll 8
;                 for (int kk = 0; kk < 128; ++kk) { const int k = wave * 128 + kk; const float w = Wp[(size_t)k * 6144];
;                     a0 += sv[k] * w; a1 += sv[1024 + k] * w; a2 += sv[2048 + k] * w; a3 += sv[3072 + k] * w; a4 += sv[4096 + k] * w; }
;                 red[(wave * 5 + 0) * 64 + lane] = a0; red[(wave * 5 + 1) * 64 + lane] = a1; red[(wave * 5 + 2) * 64 + lane] = a2; red[(wave * 5 + 3) * 64 + lane] = a3; red[(wave * 5 + 4) * 64 + lane] = a4;
	v_pk_fma_f32 v[6:7], v[88:89], v[30:31], v[6:7] op_sel_hi:[0,1,1]
	v_pk_fma_f32 v[12:13], v[88:89], v[46:47], v[12:13] op_sel_hi:[0,1,1]
	v_fmac_f32_e32 v14, v88, v55
	s_add_i32 s10, s10, 32
	v_lshl_add_u64 v[16:17], v[4:5], 0, s[8:9]
	v_add_co_u32_e64 v18, s[4:5], s77, v16
	global_load_dword v74, v[16:17], off
	s_nop 0
	v_addc_co_u32_e64 v19, s[4:5], 0, v17, s[4:5]
	v_add_co_u32_e64 v20, s[4:5], s87, v16
	s_nop 0
	v_addc_co_u32_e64 v21, s[4:5], 0, v17, s[4:5]
	v_add_co_u32_e64 v22, s[4:5], s76, v16
	s_add_u32 s8, s8, 0x30000
	s_nop 0
	v_addc_co_u32_e64 v23, s[4:5], 0, v17, s[4:5]
	s_mov_b32 s4, 0x18000
	s_nop 0
	v_add_co_u32_e64 v24, s[4:5], s4, v16
	s_addc_u32 s9, s9, 0
	s_nop 0
	v_addc_co_u32_e64 v25, s[4:5], 0, v17, s[4:5]
	s_mov_b32 s4, 0x1e000
	s_nop 0
	v_add_co_u32_e64 v26, s[4:5], s4, v16
	s_nop 0
	v_addc_co_u32_e64 v27, s[4:5], 0, v17, s[4:5]
	s_mov_b32 s4, 0x24000
	s_nop 0
	v_add_co_u32_e64 v28, s[4:5], s4, v16
	s_nop 0
	v_addc_co_u32_e64 v29, s[4:5], 0, v17, s[4:5]
	s_mov_b32 s4, 0x2a000
	s_nop 0
	v_add_co_u32_e64 v16, s[4:5], s4, v16
	s_nop 1
	v_addc_co_u32_e64 v17, s[4:5], 0, v17, s[4:5]
	global_load_dword v76, v[18:19], off
	global_load_dword v78, v[20:21], off
	global_load_dword v80, v[22:23], off
	global_load_dword v82, v[24:25], off
	global_load_dword v84, v[26:27], off
	global_load_dword v86, v[28:29], off
	global_load_dword v88, v[16:17], off
	v_mov_b32_e32 v15, s10
	ds_read_b128 v[16:19], v15
	ds_read_b128 v[20:23], v15 offset:16
	ds_read_b128 v[24:27], v15 offset:4096
	ds_read_b128 v[28:31], v15 offset:4112
	ds_read_b128 v[32:35], v15 offset:8192
	ds_read_b128 v[36:39], v15 offset:8208
	ds_read_b128 v[40:43], v15 offset:12288
	ds_read_b128 v[44:47], v15 offset:12304
	ds_read_b128 v[48:51], v15 offset:16384
	ds_read_b128 v[52:55], v15 offset:16400
	s_waitcnt lgkmcnt(9)
	v_mov_b32_e32 v72, v16
	s_waitcnt lgkmcnt(7)
	v_mov_b32_e32 v73, v24
	v_mov_b32_e32 v24, v17
	v_mov_b32_e32 v16, v18
	v_mov_b32_e32 v17, v26
	v_mov_b32_e32 v26, v19
	s_waitcnt lgkmcnt(5)
	v_mov_b32_e32 v18, v32
	s_waitcnt lgkmcnt(3)
	v_mov_b32_e32 v19, v40
	v_mov_b32_e32 v40, v33
	v_mov_b32_e32 v32, v34
	v_mov_b32_e32 v33, v42
	v_mov_b32_e32 v42, v35
	v_mov_b32_e32 v34, v20
	v_mov_b32_e32 v35, v28
	v_mov_b32_e32 v28, v21
	v_mov_b32_e32 v20, v22
	v_mov_b32_e32 v21, v30
	v_mov_b32_e32 v30, v23
	v_mov_b32_e32 v22, v36
	s_waitcnt lgkmcnt(2)
	v_mov_b32_e32 v23, v44
	v_mov_b32_e32 v44, v37
	v_mov_b32_e32 v36, v38
	v_mov_b32_e32 v37, v46
	v_mov_b32_e32 v46, v39
	s_waitcnt vmcnt(31)
	v_pk_fma_f32 v[6:7], v[90:91], v[72:73], v[6:7] op_sel_hi:[0,1,1]
	v_pk_fma_f32 v[12:13], v[90:91], v[18:19], v[12:13] op_sel_hi:[0,1,1]
	s_waitcnt lgkmcnt(1)
	v_fmac_f32_e32 v14, v90, v48
	s_waitcnt vmcnt(30)
	v_pk_fma_f32 v[6:7], v[92:93], v[24:25], v[6:7] op_sel_hi:[0,1,1]
	v_pk_fma_f32 v[12:13], v[92:93], v[40:41], v[12:13] op_sel_hi:[0,1,1]
	v_fmac_f32_e32 v14, v92, v49
	s_waitcnt vmcnt(29)
	v_pk_fma_f32 v[6:7], v[94:95], v[16:17], v[6:7] op_sel_hi:[0,1,1]
	v_pk_fma_f32 v[12:13], v[94:95], v[32:33], v[12:13] op_sel_hi:[0,1,1]
	v_fmac_f32_e32 v14, v94, v50
	s_waitcnt vmcnt(28)
	v_pk_fma_f32 v[6:7], v[96:97], v[26:27], v[6:7] op_sel_hi:[0,1,1]
	v_pk_fma_f32 v[12:13], v[96:97], v[42:43], v[12:13] op_sel_hi:[0,1,1]
	v_fmac_f32_e32 v14, v96, v51
	s_waitcnt vmcnt(27)
	v_pk_fma_f32 v[6:7], v[98:99], v[34:35], v[6:7] op_sel_hi:[0,1,1]
	v_pk_fma_f32 v[12:13], v[98:99], v[22:23], v[12:13] op_sel_hi:[0,1,1]
	s_waitcnt lgkmcnt(0)
	v_fmac_f32_e32 v14, v98, v52
	s_waitcnt vmcnt(26)
	v_pk_fma_f32 v[6:7], v[100:101], v[28:29], v[6:7] op_sel_hi:[0,1,1]
	v_pk_fma_f32 v[12:13], v[100:101], v[44:45], v[12:13] op_sel_hi:[0,1,1]
	v_fmac_f32_e32 v14, v100, v53
	s_waitcnt vmcnt(25)
	v_pk_fma_f32 v[6:7], v[102:103], v[20:21], v[6:7] op_sel_hi:[0,1,1]
	v_pk_fma_f32 v[12:13], v[102:103], v[36:37], v[12:13] op_sel_hi:[0,1,1]
	v_fmac_f32_e32 v14, v102, v54
	s_waitcnt vmcnt(24)
	v_pk_fma_f32 v[6:7], v[104:105], v[30:31], v[6:7] op_sel_hi:[0,1,1]
	v_pk_fma_f32 v[12:13], v[104:105], v[46:47], v[12:13] op_sel_hi:[0,1,1]
	v_fmac_f32_e32 v14, v104, v55
	s_add_i32 s10, s10, 32
	v_lshl_add_u64 v[16:17], v[4:5], 0, s[8:9]
	v_add_co_u32_e64 v18, s[4:5], s77, v16
	global_load_dword v90, v[16:17], off
	s_nop 0
	v_addc_co_u32_e64 v19, s[4:5], 0, v17, s[4:5]
	v_add_co_u32_e64 v20, s[4:5], s87, v16
	s_nop 0
	v_addc_co_u32_e64 v21, s[4:5], 0, v17, s[4:5]
	v_add_co_u32_e64 v22, s[4:5], s76, v16
	s_add_u32 s8, s8, 0x30000
	s_nop 0
	v_addc_co_u32_e64 v23, s[4:5], 0, v17, s[4:5]
	s_mov_b32 s4, 0x18000
	s_nop 0
	v_add_co_u32_e64 v24, s[4:5], s4, v16
	s_addc_u32 s9, s9, 0
	s_nop 0
	v_addc_co_u32_e64 v25, s[4:5], 0, v17, s[4:5]
	s_mov_b32 s4, 0x1e000
	s_nop 0
	v_add_co_u32_e64 v26, s[4:5], s4, v16
	s_nop 0
	v_addc_co_u32_e64 v27, s[4:5], 0, v17, s[4:5]
	s_mov_b32 s4, 0x24000
	s_nop 0
	v_add_co_u32_e64 v28, s[4:5], s4, v16
	s_nop 0
	v_addc_co_u32_e64 v29, s[4:5], 0, v17, s[4:5]
	s_mov_b32 s4, 0x2a000
	s_nop 0
	v_add_co_u32_e64 v16, s[4:5], s4, v16
	s_nop 1
	v_addc_co_u32_e64 v17, s[4:5], 0, v17, s[4:5]
	global_load_dword v92, v[18:19], off
	global_load_dword v94, v[20:21], off
	global_load_dword v96, v[22:23], off
	global_load_dword v98, v[24:25], off
	global_load_dword v100, v[26:27], off
	global_load_dword v102, v[28:29], off
	global_load_dword v104, v[16:17], off
	v_mov_b32_e32 v15, s10
	ds_read_b128 v[16:19], v15
	ds_read_b128 v[20:23], v15 offset:16
	ds_read_b128 v[24:27], v15 offset:4096
	ds_read_b128 v[28:31], v15 offset:4112
	ds_read_b128 v[32:35], v15 offset:8192
	ds_read_b128 v[36:39], v15 offset:8208
	ds_read_b128 v[40:43], v15 offset:12288
	ds_read_b128 v[44:47], v15 offset:12304
	ds_read_b128 v[48:51], v15 offset:16384
	ds_read_b128 v[52:55], v15 offset:16400
	s_waitcnt lgkmcnt(9)
; __global__ void __launch_bounds__(512) mega(Params p) {
;     ...
;             for (int it = bx; it < DEPTH * 96; it += G) {
;                 const int i = it / 96, nb = it % 96; const float* Wp = p.in[4] + (size_t)i * 1024 * 6144 + nb * 64 + lane;
;                 float a0 = 0.f, a1 = 0.f, a2 = 0.f, a3 = 0.f, a4 = 0.f;
; #pragma unroll 8
;                 for (int kk = 0; kk < 128; ++kk) { const int k = wave * 128 + kk; const float w = Wp[(size_t)k * 6144];
;                     a0 += sv[k] * w; a1 += sv[1024 + k] * w; a2 += sv[2048 + k] * w; a3 += sv[3072 + k] * w; a4 += sv[4096 + k] * w; }
;                 red[(wave * 5 + 0) * 64 + lane] = a0; red[(wave * 5 + 1) * 64 + lane] = a1; red[(wave * 5 + 2) * 64 + lane] = a2; red[(wave * 5 + 3) * 64 + lane] = a3; red[(wave * 5 + 4) * 64 + lane] = a4;
	v_mov_b32_e32 v72, v16
	s_waitcnt lgkmcnt(7)
	v_mov_b32_e32 v73, v24
	v_mov_b32_e32 v24, v17
	v_mov_b32_e32 v16, v18
	v_mov_b32_e32 v17, v26
	v_mov_b32_e32 v26, v19
	s_waitcnt lgkmcnt(5)
	v_mov_b32_e32 v18, v32
	s_waitcnt lgkmcnt(3)
	v_mov_b32_e32 v19, v40
	v_mov_b32_e32 v40, v33
	v_mov_b32_e32 v32, v34
	v_mov_b32_e32 v33, v42
	v_mov_b32_e32 v42, v35
	v_mov_b32_e32 v34, v20
	v_mov_b32_e32 v35, v28
	v_mov_b32_e32 v28, v21
	v_mov_b32_e32 v20, v22
	v_mov_b32_e32 v21, v30
	v_mov_b32_e32 v30, v23
	v_mov_b32_e32 v22, v36
	s_waitcnt lgkmcnt(2)
	v_mov_b32_e32 v23, v44
	v_mov_b32_e32 v44, v37
	v_mov_b32_e32 v36, v38
	v_mov_b32_e32 v37, v46
	v_mov_b32_e32 v46, v39
	s_waitcnt vmcnt(31)
	v_pk_fma_f32 v[6:7], v[106:107], v[72:73], v[6:7] op_sel_hi:[0,1,1]
	v_pk_fma_f32 v[12:13], v[106:107], v[18:19], v[12:13] op_sel_hi:[0,1,1]
	s_waitcnt lgkmcnt(1)
	v_fmac_f32_e32 v14, v106, v48
	s_waitcnt vmcnt(30)
	v_pk_fma_f32 v[6:7], v[108:109], v[24:25], v[6:7] op_sel_hi:[0,1,1]
	v_pk_fma_f32 v[12:13], v[108:109], v[40:41], v[12:13] op_sel_hi:[0,1,1]
	v_fmac_f32_e32 v14, v108, v49
	s_waitcnt vmcnt(29)
	v_pk_fma_f32 v[6:7], v[110:111], v[16:17], v[6:7] op_sel_hi:[0,1,1]
	v_pk_fma_f32 v[12:13], v[110:111], v[32:33], v[12:13] op_sel_hi:[0,1,1]
	v_fmac_f32_e32 v14, v110, v50
	s_waitcnt vmcnt(28)
	v_pk_fma_f32 v[6:7], v[112:113], v[26:27], v[6:7] op_sel_hi:[0,1,1]
	v_pk_fma_f32 v[12:13], v[112:113], v[42:43], v[12:13] op_sel_hi:[0,1,1]
	v_fmac_f32_e32 v14, v112, v51
	s_waitcnt vmcnt(27)
	v_pk_fma_f32 v[6:7], v[114:115], v[34:35], v[6:7] op_sel_hi:[0,1,1]
	v_pk_fma_f32 v[12:13], v[114:115], v[22:23], v[12:13] op_sel_hi:[0,1,1]
	s_waitcnt lgkmcnt(0)
	v_fmac_f32_e32 v14, v114, v52
	s_waitcnt vmcnt(26)
	v_pk_fma_f32 v[6:7], v[116:117], v[28:29], v[6:7] op_sel_hi:[0,1,1]
	v_pk_fma_f32 v[12:13], v[116:117], v[44:45], v[12:13] op_sel_hi:[0,1,1]
	v_fmac_f32_e32 v14, v116, v53
	s_waitcnt vmcnt(25)
	v_pk_fma_f32 v[6:7], v[118:119], v[20:21], v[6:7] op_sel_hi:[0,1,1]
	v_pk_fma_f32 v[12:13], v[118:119], v[36:37], v[12:13] op_sel_hi:[0,1,1]
	v_fmac_f32_e32 v14, v118, v54
	s_waitcnt vmcnt(24)
	v_pk_fma_f32 v[6:7], v[120:121], v[30:31], v[6:7] op_sel_hi:[0,1,1]
	v_pk_fma_f32 v[12:13], v[120:121], v[46:47], v[12:13] op_sel_hi:[0,1,1]
	v_fmac_f32_e32 v14, v120, v55
	s_add_i32 s10, s10, 32
	v_lshl_add_u64 v[16:17], v[4:5], 0, s[8:9]
	v_add_co_u32_e64 v18, s[4:5], s77, v16
	global_load_dword v106, v[16:17], off
	s_nop 0
	v_addc_co_u32_e64 v19, s[4:5], 0, v17, s[4:5]
	v_add_co_u32_e64 v20, s[4:5], s87, v16
	s_nop 0
	v_addc_co_u32_e64 v21, s[4:5], 0, v17, s[4:5]
	v_add_co_u32_e64 v22, s[4:5], s76, v16
	s_add_u32 s8, s8, 0x30000
	s_nop 0
	v_addc_co_u32_e64 v23, s[4:5], 0, v17, s[4:5]
	s_mov_b32 s4, 0x18000
	s_nop 0
	v_add_co_u32_e64 v24, s[4:5], s4, v16
	s_addc_u32 s9, s9, 0
	s_nop 0
	v_addc_co_u32_e64 v25, s[4:5], 0, v17, s[4:5]
	s_mov_b32 s4, 0x1e000
	s_nop 0
	v_add_co_u32_e64 v26, s[4:5], s4, v16
	s_nop 0
	v_addc_co_u32_e64 v27, s[4:5], 0, v17, s[4:5]
	s_mov_b32 s4, 0x24000
	s_nop 0
	v_add_co_u32_e64 v28, s[4:5], s4, v16
	s_nop 0
	v_addc_co_u32_e64 v29, s[4:5], 0, v17, s[4:5]
	s_mov_b32 s4, 0x2a000
	s_nop 0
	v_add_co_u32_e64 v16, s[4:5], s4, v16
	s_nop 1
	v_addc_co_u32_e64 v17, s[4:5], 0, v17, s[4:5]
	global_load_dword v108, v[18:19], off
	global_load_dword v110, v[20:21], off
	global_load_dword v112, v[22:23], off
	global_load_dword v114, v[24:25], off
	global_load_dword v116, v[26:27], off
	global_load_dword v118, v[28:29], off
	global_load_dword v120, v[16:17], off
	v_mov_b32_e32 v15, s10
	ds_read_b128 v[16:19], v15
	ds_read_b128 v[20:23], v15 offset:16
	ds_read_b128 v[24:27], v15 offset:4096
	ds_read_b128 v[28:31], v15 offset:4112
	ds_read_b128 v[32:35], v15 offset:8192
	ds_read_b128 v[36:39], v15 offset:8208
	ds_read_b128 v[40:43], v15 offset:12288
	ds_read_b128 v[44:47], v15 offset:12304
	ds_read_b128 v[48:51], v15 offset:16384
	ds_read_b128 v[52:55], v15 offset:16400
	s_waitcnt lgkmcnt(9)
	v_mov_b32_e32 v72, v16
	s_waitcnt lgkmcnt(7)
	v_mov_b32_e32 v73, v24
	v_mov_b32_e32 v24, v17
	v_mov_b32_e32 v16, v18
	v_mov_b32_e32 v17, v26
	v_mov_b32_e32 v26, v19
	s_waitcnt lgkmcnt(5)
	v_mov_b32_e32 v18, v32
	s_waitcnt lgkmcnt(3)
	v_mov_b32_e32 v19, v40
	v_mov_b32_e32 v40, v33
	v_mov_b32_e32 v32, v34
	v_mov_b32_e32 v33, v42
	v_mov_b32_e32 v42, v35
	v_mov_b32_e32 v34, v20
	v_mov_b32_e32 v35, v28
	v_mov_b32_e32 v28, v21
	v_mov_b32_e32 v20, v22
	v_mov_b32_e32 v21, v30
	v_mov_b32_e32 v30, v23
	v_mov_b32_e32 v22, v36
	s_waitcnt lgkmcnt(2)
	v_mov_b32_e32 v23, v44
	v_mov_b32_e32 v44, v37
	v_mov_b32_e32 v36, v38
	v_mov_b32_e32 v37, v46
	v_mov_b32_e32 v46, v39
	s_waitcnt vmcnt(31)
	v_pk_fma_f32 v[6:7], v[56:57], v[72:73], v[6:7] op_sel_hi:[0,1,1]
	v_pk_fma_f32 v[12:13], v[56:57], v[18:19], v[12:13] op_sel_hi:[0,1,1]
	s_waitcnt lgkmcnt(1)
	v_fmac_f32_e32 v14, v56, v48
	s_waitcnt vmcnt(30)
	v_pk_fma_f32 v[6:7], v[58:59], v[24:25], v[6:7] op_sel_hi:[0,1,1]
	v_pk_fma_f32 v[12:13], v[58:59], v[40:41], v[12:13] op_sel_hi:[0,1,1]
	v_fmac_f32_e32 v14, v58, v49
	s_waitcnt vmcnt(29)
	v_pk_fma_f32 v[6:7], v[60:61], v[16:17], v[6:7] op_sel_hi:[0,1,1]
	v_pk_fma_f32 v[12:13], v[60:61], v[32:33], v[12:13] op_sel_hi:[0,1,1]
	v_fmac_f32_e32 v14, v60, v50
	s_waitcnt vmcnt(28)
	v_pk_fma_f32 v[6:7], v[62:63], v[26:27], v[6:7] op_sel_hi:[0,1,1]
	v_pk_fma_f32 v[12:13], v[62:63], v[42:43], v[12:13] op_sel_hi:[0,1,1]
	v_fmac_f32_e32 v14, v62, v51
	s_waitcnt vmcnt(27)
	v_pk_fma_f32 v[6:7], v[64:65], v[34:35], v[6:7] op_sel_hi:[0,1,1]
	v_pk_fma_f32 v[12:13], v[64:65], v[22:23], v[12:13] op_sel_hi:[0,1,1]
	s_waitcnt lgkmcnt(0)
	v_fmac_f32_e32 v14, v64, v52
	s_waitcnt vmcnt(26)
; __global__ void __launch_bounds__(512) mega(Params p) {
;     ...
;             for (int it = bx; it < DEPTH * 96; it += G) {
;                 const int i = it / 96, nb = it % 96; const float* Wp = p.in[4] + (size_t)i * 1024 * 6144 + nb * 64 + lane;
;                 float a0 = 0.f, a1 = 0.f, a2 = 0.f, a3 = 0.f, a4 = 0.f;
; #pragma unroll 8
;                 for (int kk = 0; kk < 128; ++kk) { const int k = wave * 128 + kk; const float w = Wp[(size_t)k * 6144];
;                     a0 += sv[k] * w; a1 += sv[1024 + k] * w; a2 += sv[2048 + k] * w; a3 += sv[3072 + k] * w; a4 += sv[4096 + k] * w; }
	v_pk_fma_f32 v[6:7], v[66:67], v[28:29], v[6:7] op_sel_hi:[0,1,1]
	v_pk_fma_f32 v[12:13], v[66:67], v[44:45], v[12:13] op_sel_hi:[0,1,1]
	v_fmac_f32_e32 v14, v66, v53
	s_waitcnt vmcnt(25)
	v_pk_fma_f32 v[6:7], v[68:69], v[20:21], v[6:7] op_sel_hi:[0,1,1]
	v_pk_fma_f32 v[12:13], v[68:69], v[36:37], v[12:13] op_sel_hi:[0,1,1]
	v_fmac_f32_e32 v14, v68, v54
	s_waitcnt vmcnt(24)
	v_pk_fma_f32 v[6:7], v[70:71], v[30:31], v[6:7] op_sel_hi:[0,1,1]
	v_pk_fma_f32 v[12:13], v[70:71], v[46:47], v[12:13] op_sel_hi:[0,1,1]
	v_fmac_f32_e32 v14, v70, v55
	s_add_i32 s10, s10, 32
	v_lshl_add_u64 v[16:17], v[4:5], 0, s[8:9]
	v_add_co_u32_e64 v18, s[4:5], s77, v16
	global_load_dword v56, v[16:17], off
	s_nop 0
	v_addc_co_u32_e64 v19, s[4:5], 0, v17, s[4:5]
	v_add_co_u32_e64 v20, s[4:5], s87, v16
	s_nop 0
	v_addc_co_u32_e64 v21, s[4:5], 0, v17, s[4:5]
	v_add_co_u32_e64 v22, s[4:5], s76, v16
	s_add_u32 s8, s8, 0x30000
	s_nop 0
	v_addc_co_u32_e64 v23, s[4:5], 0, v17, s[4:5]
	s_mov_b32 s4, 0x18000
	s_nop 0
	v_add_co_u32_e64 v24, s[4:5], s4, v16
	s_addc_u32 s9, s9, 0
	s_nop 0
	v_addc_co_u32_e64 v25, s[4:5], 0, v17, s[4:5]
	s_mov_b32 s4, 0x1e000
	s_nop 0
	v_add_co_u32_e64 v26, s[4:5], s4, v16
	s_nop 0
	v_addc_co_u32_e64 v27, s[4:5], 0, v17, s[4:5]
	s_mov_b32 s4, 0x24000
	s_nop 0
	v_add_co_u32_e64 v28, s[4:5], s4, v16
	s_nop 0
	v_addc_co_u32_e64 v29, s[4:5], 0, v17, s[4:5]
	s_mov_b32 s4, 0x2a000
	s_nop 0
	v_add_co_u32_e64 v16, s[4:5], s4, v16
	s_nop 1
	v_addc_co_u32_e64 v17, s[4:5], 0, v17, s[4:5]
	global_load_dword v58, v[18:19], off
	global_load_dword v60, v[20:21], off
	global_load_dword v62, v[22:23], off
	global_load_dword v64, v[24:25], off
	global_load_dword v66, v[26:27], off
	global_load_dword v68, v[28:29], off
	global_load_dword v70, v[16:17], off
	v_mov_b32_e32 v15, s10
	ds_read_b128 v[16:19], v15
	ds_read_b128 v[20:23], v15 offset:16
	ds_read_b128 v[24:27], v15 offset:4096
	ds_read_b128 v[28:31], v15 offset:4112
	ds_read_b128 v[32:35], v15 offset:8192
	ds_read_b128 v[36:39], v15 offset:8208
	ds_read_b128 v[40:43], v15 offset:12288
	ds_read_b128 v[44:47], v15 offset:12304
	ds_read_b128 v[48:51], v15 offset:16384
	ds_read_b128 v[52:55], v15 offset:16400
	s_waitcnt lgkmcnt(9)
	v_mov_b32_e32 v72, v16
	s_waitcnt lgkmcnt(7)
	v_mov_b32_e32 v73, v24
	v_mov_b32_e32 v24, v17
	v_mov_b32_e32 v16, v18
	v_mov_b32_e32 v17, v26
	v_mov_b32_e32 v26, v19
	s_waitcnt lgkmcnt(5)
	v_mov_b32_e32 v18, v32
	s_waitcnt lgkmcnt(3)
	v_mov_b32_e32 v19, v40
	v_mov_b32_e32 v40, v33
	v_mov_b32_e32 v32, v34
	v_mov_b32_e32 v33, v42
	v_mov_b32_e32 v42, v35
	v_mov_b32_e32 v34, v20
	v_mov_b32_e32 v35, v28
	v_mov_b32_e32 v28, v21
	v_mov_b32_e32 v20, v22
	v_mov_b32_e32 v21, v30
	v_mov_b32_e32 v30, v23
	v_mov_b32_e32 v22, v36
	s_waitcnt lgkmcnt(2)
	v_mov_b32_e32 v23, v44
	v_mov_b32_e32 v44, v37
	v_mov_b32_e32 v36, v38
	v_mov_b32_e32 v37, v46
	v_mov_b32_e32 v46, v39
	s_waitcnt vmcnt(31)
	v_pk_fma_f32 v[6:7], v[74:75], v[72:73], v[6:7] op_sel_hi:[0,1,1]
	v_pk_fma_f32 v[12:13], v[74:75], v[18:19], v[12:13] op_sel_hi:[0,1,1]
	s_waitcnt lgkmcnt(1)
	v_fmac_f32_e32 v14, v74, v48
	s_waitcnt vmcnt(30)
	v_pk_fma_f32 v[6:7], v[76:77], v[24:25], v[6:7] op_sel_hi:[0,1,1]
	v_pk_fma_f32 v[12:13], v[76:77], v[40:41], v[12:13] op_sel_hi:[0,1,1]
	v_fmac_f32_e32 v14, v76, v49
	s_waitcnt vmcnt(29)
	v_pk_fma_f32 v[6:7], v[78:79], v[16:17], v[6:7] op_sel_hi:[0,1,1]
	v_pk_fma_f32 v[12:13], v[78:79], v[32:33], v[12:13] op_sel_hi:[0,1,1]
	v_fmac_f32_e32 v14, v78, v50
	s_waitcnt vmcnt(28)
	v_pk_fma_f32 v[6:7], v[80:81], v[26:27], v[6:7] op_sel_hi:[0,1,1]
	v_pk_fma_f32 v[12:13], v[80:81], v[42:43], v[12:13] op_sel_hi:[0,1,1]
	v_fmac_f32_e32 v14, v80, v51
	s_waitcnt vmcnt(27)
	v_pk_fma_f32 v[6:7], v[82:83], v[34:35], v[6:7] op_sel_hi:[0,1,1]
	v_pk_fma_f32 v[12:13], v[82:83], v[22:23], v[12:13] op_sel_hi:[0,1,1]
	s_waitcnt lgkmcnt(0)
	v_fmac_f32_e32 v14, v82, v52
	s_waitcnt vmcnt(26)
	v_pk_fma_f32 v[6:7], v[84:85], v[28:29], v[6:7] op_sel_hi:[0,1,1]
	v_pk_fma_f32 v[12:13], v[84:85], v[44:45], v[12:13] op_sel_hi:[0,1,1]
	v_fmac_f32_e32 v14, v84, v53
	s_waitcnt vmcnt(25)
	v_pk_fma_f32 v[6:7], v[86:87], v[20:21], v[6:7] op_sel_hi:[0,1,1]
	v_pk_fma_f32 v[12:13], v[86:87], v[36:37], v[12:13] op_sel_hi:[0,1,1]
	v_fmac_f32_e32 v14, v86, v54
	s_waitcnt vmcnt(24)
	v_pk_fma_f32 v[6:7], v[88:89], v[30:31], v[6:7] op_sel_hi:[0,1,1]
	v_pk_fma_f32 v[12:13], v[88:89], v[46:47], v[12:13] op_sel_hi:[0,1,1]
	v_fmac_f32_e32 v14, v88, v55
	s_add_i32 s10, s10, 32
	v_lshl_add_u64 v[16:17], v[4:5], 0, s[8:9]
	v_add_co_u32_e64 v18, s[4:5], s77, v16
	global_load_dword v74, v[16:17], off
	s_nop 0
	v_addc_co_u32_e64 v19, s[4:5], 0, v17, s[4:5]
	v_add_co_u32_e64 v20, s[4:5], s87, v16
	s_nop 0
	v_addc_co_u32_e64 v21, s[4:5], 0, v17, s[4:5]
	v_add_co_u32_e64 v22, s[4:5], s76, v16
	s_add_u32 s8, s8, 0x30000
	s_nop 0
	v_addc_co_u32_e64 v23, s[4:5], 0, v17, s[4:5]
	s_mov_b32 s4, 0x18000
	s_nop 0
	v_add_co_u32_e64 v24, s[4:5], s4, v16
	s_addc_u32 s9, s9, 0
	s_nop 0
	v_addc_co_u32_e64 v25, s[4:5], 0, v17, s[4:5]
	s_mov_b32 s4, 0x1e000
	s_nop 0
	v_add_co_u32_e64 v26, s[4:5], s4, v16
	s_nop 0
	v_addc_co_u32_e64 v27, s[4:5], 0, v17, s[4:5]
	s_mov_b32 s4, 0x24000
	s_nop 0
	v_add_co_u32_e64 v28, s[4:5], s4, v16
	s_nop 0
	v_addc_co_u32_e64 v29, s[4:5], 0, v17, s[4:5]
	s_mov_b32 s4, 0x2a000
	s_nop 0
	v_add_co_u32_e64 v16, s[4:5], s4, v16
	s_nop 1
	v_addc_co_u32_e64 v17, s[4:5], 0, v17, s[4:5]
	global_load_dword v76, v[18:19], off
	global_load_dword v78, v[20:21], off
	global_load_dword v80, v[22:23], off
	global_load_dword v82, v[24:25], off
	global_load_dword v84, v[26:27], off
	global_load_dword v86, v[28:29], off
	global_load_dword v88, v[16:17], off
	v_mov_b32_e32 v15, s10
	ds_read_b128 v[16:19], v15
	ds_read_b128 v[20:23], v15 offset:16
	ds_read_b128 v[24:27], v15 offset:4096
	ds_read_b128 v[28:31], v15 offset:4112
	ds_read_b128 v[32:35], v15 offset:8192
	ds_read_b128 v[36:39], v15 offset:8208
	ds_read_b128 v[40:43], v15 offset:12288
	ds_read_b128 v[44:47], v15 offset:12304
	ds_read_b128 v[48:51], v15 offset:16384
	ds_read_b128 v[52:55], v15 offset:16400
	s_waitcnt lgkmcnt(9)
; __global__ void __launch_bounds__(512) mega(Params p) {
;     ...
;             for (int it = bx; it < DEPTH * 96; it += G) {
;                 const int i = it / 96, nb = it % 96; const float* Wp = p.in[4] + (size_t)i * 1024 * 6144 + nb * 64 + lane;
;                 float a0 = 0.f, a1 = 0.f, a2 = 0.f, a3 = 0.f, a4 = 0.f;
; #pragma unroll 8
;                 for (int kk = 0; kk < 128; ++kk) { const int k = wave * 128 + kk; const float w = Wp[(size_t)k * 6144];
;                     a0 += sv[k] * w; a1 += sv[1024 + k] * w; a2 += sv[2048 + k] * w; a3 += sv[3072 + k] * w; a4 += sv[4096 + k] * w; }
	v_mov_b32_e32 v72, v16
	s_waitcnt lgkmcnt(7)
	v_mov_b32_e32 v73, v24
	v_mov_b32_e32 v24, v17
	v_mov_b32_e32 v16, v18
	v_mov_b32_e32 v17, v26
	v_mov_b32_e32 v26, v19
	s_waitcnt lgkmcnt(5)
	v_mov_b32_e32 v18, v32
	s_waitcnt lgkmcnt(3)
	v_mov_b32_e32 v19, v40
	v_mov_b32_e32 v40, v33
	v_mov_b32_e32 v32, v34
	v_mov_b32_e32 v33, v42
	v_mov_b32_e32 v42, v35
	v_mov_b32_e32 v34, v20
	v_mov_b32_e32 v35, v28
	v_mov_b32_e32 v28, v21
	v_mov_b32_e32 v20, v22
	v_mov_b32_e32 v21, v30
	v_mov_b32_e32 v30, v23
	v_mov_b32_e32 v22, v36
	s_waitcnt lgkmcnt(2)
	v_mov_b32_e32 v23, v44
	v_mov_b32_e32 v44, v37
	v_mov_b32_e32 v36, v38
	v_mov_b32_e32 v37, v46
	v_mov_b32_e32 v46, v39
	s_waitcnt vmcnt(31)
	v_pk_fma_f32 v[6:7], v[90:91], v[72:73], v[6:7] op_sel_hi:[0,1,1]
	v_pk_fma_f32 v[12:13], v[90:91], v[18:19], v[12:13] op_sel_hi:[0,1,1]
	s_waitcnt lgkmcnt(1)
	v_fmac_f32_e32 v14, v90, v48
	s_waitcnt vmcnt(30)
	v_pk_fma_f32 v[6:7], v[92:93], v[24:25], v[6:7] op_sel_hi:[0,1,1]
	v_pk_fma_f32 v[12:13], v[92:93], v[40:41], v[12:13] op_sel_hi:[0,1,1]
	v_fmac_f32_e32 v14, v92, v49
	s_waitcnt vmcnt(29)
	v_pk_fma_f32 v[6:7], v[94:95], v[16:17], v[6:7] op_sel_hi:[0,1,1]
	v_pk_fma_f32 v[12:13], v[94:95], v[32:33], v[12:13] op_sel_hi:[0,1,1]
	v_fmac_f32_e32 v14, v94, v50
	s_waitcnt vmcnt(28)
	v_pk_fma_f32 v[6:7], v[96:97], v[26:27], v[6:7] op_sel_hi:[0,1,1]
	v_pk_fma_f32 v[12:13], v[96:97], v[42:43], v[12:13] op_sel_hi:[0,1,1]
	v_fmac_f32_e32 v14, v96, v51
	s_waitcnt vmcnt(27)
	v_pk_fma_f32 v[6:7], v[98:99], v[34:35], v[6:7] op_sel_hi:[0,1,1]
	v_pk_fma_f32 v[12:13], v[98:99], v[22:23], v[12:13] op_sel_hi:[0,1,1]
	s_waitcnt lgkmcnt(0)
	v_fmac_f32_e32 v14, v98, v52
	s_waitcnt vmcnt(26)
	v_pk_fma_f32 v[6:7], v[100:101], v[28:29], v[6:7] op_sel_hi:[0,1,1]
	v_pk_fma_f32 v[12:13], v[100:101], v[44:45], v[12:13] op_sel_hi:[0,1,1]
	v_fmac_f32_e32 v14, v100, v53
	s_waitcnt vmcnt(25)
	v_pk_fma_f32 v[6:7], v[102:103], v[20:21], v[6:7] op_sel_hi:[0,1,1]
	v_pk_fma_f32 v[12:13], v[102:103], v[36:37], v[12:13] op_sel_hi:[0,1,1]
	v_fmac_f32_e32 v14, v102, v54
	s_waitcnt vmcnt(24)
	v_pk_fma_f32 v[6:7], v[104:105], v[30:31], v[6:7] op_sel_hi:[0,1,1]
	v_pk_fma_f32 v[12:13], v[104:105], v[46:47], v[12:13] op_sel_hi:[0,1,1]
	v_fmac_f32_e32 v14, v104, v55
	s_add_i32 s10, s10, 32
	v_lshl_add_u64 v[16:17], v[4:5], 0, s[8:9]
	v_add_co_u32_e64 v18, s[4:5], s77, v16
	global_load_dword v90, v[16:17], off
	s_nop 0
	v_addc_co_u32_e64 v19, s[4:5], 0, v17, s[4:5]
	v_add_co_u32_e64 v20, s[4:5], s87, v16
	s_nop 0
	v_addc_co_u32_e64 v21, s[4:5], 0, v17, s[4:5]
	v_add_co_u32_e64 v22, s[4:5], s76, v16
	s_add_u32 s8, s8, 0x30000
	s_nop 0
	v_addc_co_u32_e64 v23, s[4:5], 0, v17, s[4:5]
	s_mov_b32 s4, 0x18000
	s_nop 0
	v_add_co_u32_e64 v24, s[4:5], s4, v16
	s_addc_u32 s9, s9, 0
	s_nop 0
	v_addc_co_u32_e64 v25, s[4:5], 0, v17, s[4:5]
	s_mov_b32 s4, 0x1e000
	s_nop 0
	v_add_co_u32_e64 v26, s[4:5], s4, v16
	s_nop 0
	v_addc_co_u32_e64 v27, s[4:5], 0, v17, s[4:5]
	s_mov_b32 s4, 0x24000
	s_nop 0
	v_add_co_u32_e64 v28, s[4:5], s4, v16
	s_nop 0
	v_addc_co_u32_e64 v29, s[4:5], 0, v17, s[4:5]
	s_mov_b32 s4, 0x2a000
	s_nop 0
	v_add_co_u32_e64 v16, s[4:5], s4, v16
	s_nop 1
	v_addc_co_u32_e64 v17, s[4:5], 0, v17, s[4:5]
	global_load_dword v92, v[18:19], off
	global_load_dword v94, v[20:21], off
	global_load_dword v96, v[22:23], off
	global_load_dword v98, v[24:25], off
	global_load_dword v100, v[26:27], off
	global_load_dword v102, v[28:29], off
	global_load_dword v104, v[16:17], off
	v_mov_b32_e32 v15, s10
	ds_read_b128 v[16:19], v15
	ds_read_b128 v[20:23], v15 offset:16
	ds_read_b128 v[24:27], v15 offset:4096
	ds_read_b128 v[28:31], v15 offset:4112
	ds_read_b128 v[32:35], v15 offset:8192
	ds_read_b128 v[36:39], v15 offset:8208
	ds_read_b128 v[40:43], v15 offset:12288
	ds_read_b128 v[44:47], v15 offset:12304
	ds_read_b128 v[48:51], v15 offset:16384
	ds_read_b128 v[52:55], v15 offset:16400
	s_waitcnt lgkmcnt(9)
	v_mov_b32_e32 v72, v16
	s_waitcnt lgkmcnt(7)
	v_mov_b32_e32 v73, v24
	v_mov_b32_e32 v24, v17
	v_mov_b32_e32 v16, v18
	v_mov_b32_e32 v17, v26
	v_mov_b32_e32 v26, v19
	s_waitcnt lgkmcnt(5)
	v_mov_b32_e32 v18, v32
	s_waitcnt lgkmcnt(3)
	v_mov_b32_e32 v19, v40
	v_mov_b32_e32 v40, v33
	v_mov_b32_e32 v32, v34
	v_mov_b32_e32 v33, v42
	v_mov_b32_e32 v42, v35
	v_mov_b32_e32 v34, v20
	v_mov_b32_e32 v35, v28
	v_mov_b32_e32 v28, v21
	v_mov_b32_e32 v20, v22
	v_mov_b32_e32 v21, v30
	v_mov_b32_e32 v30, v23
	v_mov_b32_e32 v22, v36
	s_waitcnt lgkmcnt(2)
	v_mov_b32_e32 v23, v44
	v_mov_b32_e32 v44, v37
	v_mov_b32_e32 v36, v38
	v_mov_b32_e32 v37, v46
	v_mov_b32_e32 v46, v39
	s_waitcnt vmcnt(31)
	v_pk_fma_f32 v[6:7], v[106:107], v[72:73], v[6:7] op_sel_hi:[0,1,1]
	v_pk_fma_f32 v[12:13], v[106:107], v[18:19], v[12:13] op_sel_hi:[0,1,1]
	s_waitcnt lgkmcnt(1)
	v_fmac_f32_e32 v14, v106, v48
	s_waitcnt vmcnt(30)
	v_pk_fma_f32 v[6:7], v[108:109], v[24:25], v[6:7] op_sel_hi:[0,1,1]
	v_pk_fma_f32 v[12:13], v[108:109], v[40:41], v[12:13] op_sel_hi:[0,1,1]
	v_fmac_f32_e32 v14, v108, v49
	s_waitcnt vmcnt(29)
	v_pk_fma_f32 v[6:7], v[110:111], v[16:17], v[6:7] op_sel_hi:[0,1,1]
	v_pk_fma_f32 v[12:13], v[110:111], v[32:33], v[12:13] op_sel_hi:[0,1,1]
	v_fmac_f32_e32 v14, v110, v50
	s_waitcnt vmcnt(28)
	v_pk_fma_f32 v[6:7], v[112:113], v[26:27], v[6:7] op_sel_hi:[0,1,1]
	v_pk_fma_f32 v[12:13], v[112:113], v[42:43], v[12:13] op_sel_hi:[0,1,1]
	v_fmac_f32_e32 v14, v112, v51
	s_waitcnt vmcnt(27)
	v_pk_fma_f32 v[6:7], v[114:115], v[34:35], v[6:7] op_sel_hi:[0,1,1]
	v_pk_fma_f32 v[12:13], v[114:115], v[22:23], v[12:13] op_sel_hi:[0,1,1]
	s_waitcnt lgkmcnt(0)
	v_fmac_f32_e32 v14, v114, v52
	s_waitcnt vmcnt(26)
; __global__ void __launch_bounds__(512) mega(Params p) {
;     ...
;             for (int it = bx; it < DEPTH * 96; it += G) {
;                 const int i = it / 96, nb = it % 96; const float* Wp = p.in[4] + (size_t)i * 1024 * 6144 + nb * 64 + lane;
;                 float a0 = 0.f, a1 = 0.f, a2 = 0.f, a3 = 0.f, a4 = 0.f;
; #pragma unroll 8
;                 for (int kk = 0; kk < 128; ++kk) { const int k = wave * 128 + kk; const float w = Wp[(size_t)k * 6144];
;                     a0 += sv[k] * w; a1 += sv[1024 + k] * w; a2 += sv[2048 + k] * w; a3 += sv[3072 + k] * w; a4 += sv[4096 + k] * w; }
	v_pk_fma_f32 v[6:7], v[116:117], v[28:29], v[6:7] op_sel_hi:[0,1,1]
	v_pk_fma_f32 v[12:13], v[116:117], v[44:45], v[12:13] op_sel_hi:[0,1,1]
	v_fmac_f32_e32 v14, v116, v53
	s_waitcnt vmcnt(25)
	v_pk_fma_f32 v[6:7], v[118:119], v[20:21], v[6:7] op_sel_hi:[0,1,1]
	v_pk_fma_f32 v[12:13], v[118:119], v[36:37], v[12:13] op_sel_hi:[0,1,1]
	v_fmac_f32_e32 v14, v118, v54
	s_waitcnt vmcnt(24)
	v_pk_fma_f32 v[6:7], v[120:121], v[30:31], v[6:7] op_sel_hi:[0,1,1]
	v_pk_fma_f32 v[12:13], v[120:121], v[46:47], v[12:13] op_sel_hi:[0,1,1]
	v_fmac_f32_e32 v14, v120, v55
	s_add_i32 s10, s10, 32
	v_lshl_add_u64 v[16:17], v[4:5], 0, s[8:9]
	v_add_co_u32_e64 v18, s[4:5], s77, v16
	global_load_dword v106, v[16:17], off
	s_nop 0
	v_addc_co_u32_e64 v19, s[4:5], 0, v17, s[4:5]
	v_add_co_u32_e64 v20, s[4:5], s87, v16
	s_nop 0
	v_addc_co_u32_e64 v21, s[4:5], 0, v17, s[4:5]
	v_add_co_u32_e64 v22, s[4:5], s76, v16
	s_add_u32 s8, s8, 0x30000
	s_nop 0
	v_addc_co_u32_e64 v23, s[4:5], 0, v17, s[4:5]
	s_mov_b32 s4, 0x18000
	s_nop 0
	v_add_co_u32_e64 v24, s[4:5], s4, v16
	s_addc_u32 s9, s9, 0
	s_nop 0
	v_addc_co_u32_e64 v25, s[4:5], 0, v17, s[4:5]
	s_mov_b32 s4, 0x1e000
	s_nop 0
	v_add_co_u32_e64 v26, s[4:5], s4, v16
	s_nop 0
	v_addc_co_u32_e64 v27, s[4:5], 0, v17, s[4:5]
	s_mov_b32 s4, 0x24000
	s_nop 0
	v_add_co_u32_e64 v28, s[4:5], s4, v16
	s_nop 0
	v_addc_co_u32_e64 v29, s[4:5], 0, v17, s[4:5]
	s_mov_b32 s4, 0x2a000
	s_nop 0
	v_add_co_u32_e64 v16, s[4:5], s4, v16
	s_nop 1
	v_addc_co_u32_e64 v17, s[4:5], 0, v17, s[4:5]
	global_load_dword v108, v[18:19], off
	global_load_dword v110, v[20:21], off
	global_load_dword v112, v[22:23], off
	global_load_dword v114, v[24:25], off
	global_load_dword v116, v[26:27], off
	global_load_dword v118, v[28:29], off
	global_load_dword v120, v[16:17], off
	v_mov_b32_e32 v15, s10
	ds_read_b128 v[16:19], v15
	ds_read_b128 v[20:23], v15 offset:16
	ds_read_b128 v[24:27], v15 offset:4096
	ds_read_b128 v[28:31], v15 offset:4112
	ds_read_b128 v[32:35], v15 offset:8192
	ds_read_b128 v[36:39], v15 offset:8208
	ds_read_b128 v[40:43], v15 offset:12288
	ds_read_b128 v[44:47], v15 offset:12304
	ds_read_b128 v[48:51], v15 offset:16384
	ds_read_b128 v[52:55], v15 offset:16400
	s_waitcnt lgkmcnt(9)
	v_mov_b32_e32 v72, v16
	s_waitcnt lgkmcnt(7)
	v_mov_b32_e32 v73, v24
	v_mov_b32_e32 v24, v17
	v_mov_b32_e32 v16, v18
	v_mov_b32_e32 v17, v26
	v_mov_b32_e32 v26, v19
	s_waitcnt lgkmcnt(5)
	v_mov_b32_e32 v18, v32
	s_waitcnt lgkmcnt(3)
	v_mov_b32_e32 v19, v40
	v_mov_b32_e32 v40, v33
	v_mov_b32_e32 v32, v34
	v_mov_b32_e32 v33, v42
	v_mov_b32_e32 v42, v35
	v_mov_b32_e32 v34, v20
	v_mov_b32_e32 v35, v28
	v_mov_b32_e32 v28, v21
	v_mov_b32_e32 v20, v22
	v_mov_b32_e32 v21, v30
	v_mov_b32_e32 v30, v23
	v_mov_b32_e32 v22, v36
	s_waitcnt lgkmcnt(2)
	v_mov_b32_e32 v23, v44
	v_mov_b32_e32 v44, v37
	v_mov_b32_e32 v36, v38
	v_mov_b32_e32 v37, v46
	v_mov_b32_e32 v46, v39
	s_waitcnt vmcnt(31)
	v_pk_fma_f32 v[6:7], v[56:57], v[72:73], v[6:7] op_sel_hi:[0,1,1]
	v_pk_fma_f32 v[12:13], v[56:57], v[18:19], v[12:13] op_sel_hi:[0,1,1]
	s_waitcnt lgkmcnt(1)
	v_fmac_f32_e32 v14, v56, v48
	s_waitcnt vmcnt(30)
	v_pk_fma_f32 v[6:7], v[58:59], v[24:25], v[6:7] op_sel_hi:[0,1,1]
	v_pk_fma_f32 v[12:13], v[58:59], v[40:41], v[12:13] op_sel_hi:[0,1,1]
	v_fmac_f32_e32 v14, v58, v49
	s_waitcnt vmcnt(29)
	v_pk_fma_f32 v[6:7], v[60:61], v[16:17], v[6:7] op_sel_hi:[0,1,1]
	v_pk_fma_f32 v[12:13], v[60:61], v[32:33], v[12:13] op_sel_hi:[0,1,1]
	v_fmac_f32_e32 v14, v60, v50
	s_waitcnt vmcnt(28)
	v_pk_fma_f32 v[6:7], v[62:63], v[26:27], v[6:7] op_sel_hi:[0,1,1]
	v_pk_fma_f32 v[12:13], v[62:63], v[42:43], v[12:13] op_sel_hi:[0,1,1]
	v_fmac_f32_e32 v14, v62, v51
	s_waitcnt vmcnt(27)
	v_pk_fma_f32 v[6:7], v[64:65], v[34:35], v[6:7] op_sel_hi:[0,1,1]
	v_pk_fma_f32 v[12:13], v[64:65], v[22:23], v[12:13] op_sel_hi:[0,1,1]
	s_waitcnt lgkmcnt(0)
	v_fmac_f32_e32 v14, v64, v52
	s_waitcnt vmcnt(26)
	v_pk_fma_f32 v[6:7], v[66:67], v[28:29], v[6:7] op_sel_hi:[0,1,1]
	v_pk_fma_f32 v[12:13], v[66:67], v[44:45], v[12:13] op_sel_hi:[0,1,1]
	v_fmac_f32_e32 v14, v66, v53
	s_waitcnt vmcnt(25)
	v_pk_fma_f32 v[6:7], v[68:69], v[20:21], v[6:7] op_sel_hi:[0,1,1]
	v_pk_fma_f32 v[12:13], v[68:69], v[36:37], v[12:13] op_sel_hi:[0,1,1]
	v_fmac_f32_e32 v14, v68, v54
	s_waitcnt vmcnt(24)
	v_pk_fma_f32 v[6:7], v[70:71], v[30:31], v[6:7] op_sel_hi:[0,1,1]
	v_pk_fma_f32 v[12:13], v[70:71], v[46:47], v[12:13] op_sel_hi:[0,1,1]
	v_fmac_f32_e32 v14, v70, v55
	s_add_i32 s10, s10, 32
	v_lshl_add_u64 v[16:17], v[4:5], 0, s[8:9]
	v_add_co_u32_e64 v18, s[4:5], s77, v16
	global_load_dword v56, v[16:17], off
	s_nop 0
	v_addc_co_u32_e64 v19, s[4:5], 0, v17, s[4:5]
	v_add_co_u32_e64 v20, s[4:5], s87, v16
	s_nop 0
	v_addc_co_u32_e64 v21, s[4:5], 0, v17, s[4:5]
	v_add_co_u32_e64 v22, s[4:5], s76, v16
	s_add_u32 s8, s8, 0x30000
	s_nop 0
	v_addc_co_u32_e64 v23, s[4:5], 0, v17, s[4:5]
	s_mov_b32 s4, 0x18000
	s_nop 0
	v_add_co_u32_e64 v24, s[4:5], s4, v16
	s_addc_u32 s9, s9, 0
	s_nop 0
	v_addc_co_u32_e64 v25, s[4:5], 0, v17, s[4:5]
	s_mov_b32 s4, 0x1e000
	s_nop 0
	v_add_co_u32_e64 v26, s[4:5], s4, v16
	s_nop 0
	v_addc_co_u32_e64 v27, s[4:5], 0, v17, s[4:5]
	s_mov_b32 s4, 0x24000
	s_nop 0
	v_add_co_u32_e64 v28, s[4:5], s4, v16
	s_nop 0
	v_addc_co_u32_e64 v29, s[4:5], 0, v17, s[4:5]
	s_mov_b32 s4, 0x2a000
	s_nop 0
	v_add_co_u32_e64 v16, s[4:5], s4, v16
	s_nop 1
	v_addc_co_u32_e64 v17, s[4:5], 0, v17, s[4:5]
	global_load_dword v58, v[18:19], off
	global_load_dword v60, v[20:21], off
	global_load_dword v62, v[22:23], off
	global_load_dword v64, v[24:25], off
	global_load_dword v66, v[26:27], off
	global_load_dword v68, v[28:29], off
	global_load_dword v70, v[16:17], off
	v_mov_b32_e32 v15, s10
	ds_read_b128 v[16:19], v15
	ds_read_b128 v[20:23], v15 offset:16
	ds_read_b128 v[24:27], v15 offset:4096
	ds_read_b128 v[28:31], v15 offset:4112
	ds_read_b128 v[32:35], v15 offset:8192
	ds_read_b128 v[36:39], v15 offset:8208
	ds_read_b128 v[40:43], v15 offset:12288
	ds_read_b128 v[44:47], v15 offset:12304
	ds_read_b128 v[48:51], v15 offset:16384
	ds_read_b128 v[52:55], v15 offset:16400
	s_waitcnt lgkmcnt(9)
; __global__ void __launch_bounds__(512) mega(Params p) {
;     ...
;             for (int it = bx; it < DEPTH * 96; it += G) {
;                 const int i = it / 96, nb = it % 96; const float* Wp = p.in[4] + (size_t)i * 1024 * 6144 + nb * 64 + lane;
;                 float a0 = 0.f, a1 = 0.f, a2 = 0.f, a3 = 0.f, a4 = 0.f;
; #pragma unroll 8
;                 for (int kk = 0; kk < 128; ++kk) { const int k = wave * 128 + kk; const float w = Wp[(size_t)k * 6144];
;                     a0 += sv[k] * w; a1 += sv[1024 + k] * w; a2 += sv[2048 + k] * w; a3 += sv[3072 + k] * w; a4 += sv[4096 + k] * w; }
	v_mov_b32_e32 v72, v16
	s_waitcnt lgkmcnt(7)
	v_mov_b32_e32 v73, v24
	v_mov_b32_e32 v24, v17
	v_mov_b32_e32 v16, v18
	v_mov_b32_e32 v17, v26
	v_mov_b32_e32 v26, v19
	s_waitcnt lgkmcnt(5)
	v_mov_b32_e32 v18, v32
	s_waitcnt lgkmcnt(3)
	v_mov_b32_e32 v19, v40
	v_mov_b32_e32 v40, v33
	v_mov_b32_e32 v32, v34
	v_mov_b32_e32 v33, v42
	v_mov_b32_e32 v42, v35
	v_mov_b32_e32 v34, v20
	v_mov_b32_e32 v35, v28
	v_mov_b32_e32 v28, v21
	v_mov_b32_e32 v20, v22
	v_mov_b32_e32 v21, v30
	v_mov_b32_e32 v30, v23
	v_mov_b32_e32 v22, v36
	s_waitcnt lgkmcnt(2)
	v_mov_b32_e32 v23, v44
	v_mov_b32_e32 v44, v37
	v_mov_b32_e32 v36, v38
	v_mov_b32_e32 v37, v46
	v_mov_b32_e32 v46, v39
	s_waitcnt vmcnt(31)
	v_pk_fma_f32 v[6:7], v[74:75], v[72:73], v[6:7] op_sel_hi:[0,1,1]
	v_pk_fma_f32 v[12:13], v[74:75], v[18:19], v[12:13] op_sel_hi:[0,1,1]
	s_waitcnt lgkmcnt(1)
	v_fmac_f32_e32 v14, v74, v48
	s_waitcnt vmcnt(30)
	v_pk_fma_f32 v[6:7], v[76:77], v[24:25], v[6:7] op_sel_hi:[0,1,1]
	v_pk_fma_f32 v[12:13], v[76:77], v[40:41], v[12:13] op_sel_hi:[0,1,1]
	v_fmac_f32_e32 v14, v76, v49
	s_waitcnt vmcnt(29)
	v_pk_fma_f32 v[6:7], v[78:79], v[16:17], v[6:7] op_sel_hi:[0,1,1]
	v_pk_fma_f32 v[12:13], v[78:79], v[32:33], v[12:13] op_sel_hi:[0,1,1]
	v_fmac_f32_e32 v14, v78, v50
	s_waitcnt vmcnt(28)
	v_pk_fma_f32 v[6:7], v[80:81], v[26:27], v[6:7] op_sel_hi:[0,1,1]
	v_pk_fma_f32 v[12:13], v[80:81], v[42:43], v[12:13] op_sel_hi:[0,1,1]
	v_fmac_f32_e32 v14, v80, v51
	s_waitcnt vmcnt(27)
	v_pk_fma_f32 v[6:7], v[82:83], v[34:35], v[6:7] op_sel_hi:[0,1,1]
	v_pk_fma_f32 v[12:13], v[82:83], v[22:23], v[12:13] op_sel_hi:[0,1,1]
	s_waitcnt lgkmcnt(0)
	v_fmac_f32_e32 v14, v82, v52
	s_waitcnt vmcnt(26)
	v_pk_fma_f32 v[6:7], v[84:85], v[28:29], v[6:7] op_sel_hi:[0,1,1]
	v_pk_fma_f32 v[12:13], v[84:85], v[44:45], v[12:13] op_sel_hi:[0,1,1]
	v_fmac_f32_e32 v14, v84, v53
	s_waitcnt vmcnt(25)
	v_pk_fma_f32 v[6:7], v[86:87], v[20:21], v[6:7] op_sel_hi:[0,1,1]
	v_pk_fma_f32 v[12:13], v[86:87], v[36:37], v[12:13] op_sel_hi:[0,1,1]
	v_fmac_f32_e32 v14, v86, v54
	s_waitcnt vmcnt(24)
	v_pk_fma_f32 v[6:7], v[88:89], v[30:31], v[6:7] op_sel_hi:[0,1,1]
	v_pk_fma_f32 v[12:13], v[88:89], v[46:47], v[12:13] op_sel_hi:[0,1,1]
	v_fmac_f32_e32 v14, v88, v55
	s_add_i32 s10, s10, 32
	v_lshl_add_u64 v[16:17], v[4:5], 0, s[8:9]
	v_add_co_u32_e64 v18, s[4:5], s77, v16
	global_load_dword v74, v[16:17], off
	s_nop 0
	v_addc_co_u32_e64 v19, s[4:5], 0, v17, s[4:5]
	v_add_co_u32_e64 v20, s[4:5], s87, v16
	s_nop 0
	v_addc_co_u32_e64 v21, s[4:5], 0, v17, s[4:5]
	v_add_co_u32_e64 v22, s[4:5], s76, v16
	s_add_u32 s8, s8, 0x30000
	s_nop 0
	v_addc_co_u32_e64 v23, s[4:5], 0, v17, s[4:5]
	s_mov_b32 s4, 0x18000
	s_nop 0
	v_add_co_u32_e64 v24, s[4:5], s4, v16
	s_addc_u32 s9, s9, 0
	s_nop 0
	v_addc_co_u32_e64 v25, s[4:5], 0, v17, s[4:5]
	s_mov_b32 s4, 0x1e000
	s_nop 0
	v_add_co_u32_e64 v26, s[4:5], s4, v16
	s_nop 0
	v_addc_co_u32_e64 v27, s[4:5], 0, v17, s[4:5]
	s_mov_b32 s4, 0x24000
	s_nop 0
	v_add_co_u32_e64 v28, s[4:5], s4, v16
	s_nop 0
	v_addc_co_u32_e64 v29, s[4:5], 0, v17, s[4:5]
	s_mov_b32 s4, 0x2a000
	s_nop 0
	v_add_co_u32_e64 v16, s[4:5], s4, v16
	s_nop 1
	v_addc_co_u32_e64 v17, s[4:5], 0, v17, s[4:5]
	global_load_dword v76, v[18:19], off
	global_load_dword v78, v[20:21], off
	global_load_dword v80, v[22:23], off
	global_load_dword v82, v[24:25], off
	global_load_dword v84, v[26:27], off
	global_load_dword v86, v[28:29], off
	global_load_dword v88, v[16:17], off
	v_mov_b32_e32 v15, s10
	ds_read_b128 v[16:19], v15
	ds_read_b128 v[20:23], v15 offset:16
	ds_read_b128 v[24:27], v15 offset:4096
	ds_read_b128 v[28:31], v15 offset:4112
	ds_read_b128 v[32:35], v15 offset:8192
	ds_read_b128 v[36:39], v15 offset:8208
	ds_read_b128 v[40:43], v15 offset:12288
	ds_read_b128 v[44:47], v15 offset:12304
	ds_read_b128 v[48:51], v15 offset:16384
	ds_read_b128 v[52:55], v15 offset:16400
	s_waitcnt lgkmcnt(9)
	v_mov_b32_e32 v72, v16
	s_waitcnt lgkmcnt(7)
	v_mov_b32_e32 v73, v24
	v_mov_b32_e32 v24, v17
	v_mov_b32_e32 v16, v18
	v_mov_b32_e32 v17, v26
	v_mov_b32_e32 v26, v19
	s_waitcnt lgkmcnt(5)
	v_mov_b32_e32 v18, v32
	s_waitcnt lgkmcnt(3)
	v_mov_b32_e32 v19, v40
	v_mov_b32_e32 v40, v33
	v_mov_b32_e32 v32, v34
	v_mov_b32_e32 v33, v42
	v_mov_b32_e32 v42, v35
	v_mov_b32_e32 v34, v20
	v_mov_b32_e32 v35, v28
	v_mov_b32_e32 v28, v21
	v_mov_b32_e32 v20, v22
	v_mov_b32_e32 v21, v30
	v_mov_b32_e32 v30, v23
	v_mov_b32_e32 v22, v36
	s_waitcnt lgkmcnt(2)
	v_mov_b32_e32 v23, v44
	v_mov_b32_e32 v44, v37
	v_mov_b32_e32 v36, v38
	v_mov_b32_e32 v37, v46
	v_mov_b32_e32 v46, v39
	s_waitcnt vmcnt(31)
	v_pk_fma_f32 v[6:7], v[90:91], v[72:73], v[6:7] op_sel_hi:[0,1,1]
	v_pk_fma_f32 v[12:13], v[90:91], v[18:19], v[12:13] op_sel_hi:[0,1,1]
	s_waitcnt lgkmcnt(1)
	v_fmac_f32_e32 v14, v90, v48
	s_waitcnt vmcnt(30)
	v_pk_fma_f32 v[6:7], v[92:93], v[24:25], v[6:7] op_sel_hi:[0,1,1]
	v_pk_fma_f32 v[12:13], v[92:93], v[40:41], v[12:13] op_sel_hi:[0,1,1]
	v_fmac_f32_e32 v14, v92, v49
	s_waitcnt vmcnt(29)
	v_pk_fma_f32 v[6:7], v[94:95], v[16:17], v[6:7] op_sel_hi:[0,1,1]
	v_pk_fma_f32 v[12:13], v[94:95], v[32:33], v[12:13] op_sel_hi:[0,1,1]
	v_fmac_f32_e32 v14, v94, v50
	s_waitcnt vmcnt(28)
	v_pk_fma_f32 v[6:7], v[96:97], v[26:27], v[6:7] op_sel_hi:[0,1,1]
	v_pk_fma_f32 v[12:13], v[96:97], v[42:43], v[12:13] op_sel_hi:[0,1,1]
	v_fmac_f32_e32 v14, v96, v51
	s_waitcnt vmcnt(27)
	v_pk_fma_f32 v[6:7], v[98:99], v[34:35], v[6:7] op_sel_hi:[0,1,1]
	v_pk_fma_f32 v[12:13], v[98:99], v[22:23], v[12:13] op_sel_hi:[0,1,1]
	s_waitcnt lgkmcnt(0)
	v_fmac_f32_e32 v14, v98, v52
	s_waitcnt vmcnt(26)
; __global__ void __launch_bounds__(512) mega(Params p) {
;     ...
;             for (int it = bx; it < DEPTH * 96; it += G) {
;                 const int i = it / 96, nb = it % 96; const float* Wp = p.in[4] + (size_t)i * 1024 * 6144 + nb * 64 + lane;
;                 float a0 = 0.f, a1 = 0.f, a2 = 0.f, a3 = 0.f, a4 = 0.f;
; #pragma unroll 8
;                 for (int kk = 0; kk < 128; ++kk) { const int k = wave * 128 + kk; const float w = Wp[(size_t)k * 6144];
;                     a0 += sv[k] * w; a1 += sv[1024 + k] * w; a2 += sv[2048 + k] * w; a3 += sv[3072 + k] * w; a4 += sv[4096 + k] * w; }
	v_pk_fma_f32 v[6:7], v[100:101], v[28:29], v[6:7] op_sel_hi:[0,1,1]
	v_pk_fma_f32 v[12:13], v[100:101], v[44:45], v[12:13] op_sel_hi:[0,1,1]
	v_fmac_f32_e32 v14, v100, v53
	s_waitcnt vmcnt(25)
	v_pk_fma_f32 v[6:7], v[102:103], v[20:21], v[6:7] op_sel_hi:[0,1,1]
	v_pk_fma_f32 v[12:13], v[102:103], v[36:37], v[12:13] op_sel_hi:[0,1,1]
	v_fmac_f32_e32 v14, v102, v54
	s_waitcnt vmcnt(24)
	v_pk_fma_f32 v[6:7], v[104:105], v[30:31], v[6:7] op_sel_hi:[0,1,1]
	v_pk_fma_f32 v[12:13], v[104:105], v[46:47], v[12:13] op_sel_hi:[0,1,1]
	v_fmac_f32_e32 v14, v104, v55
	s_add_i32 s10, s10, 32
	v_lshl_add_u64 v[16:17], v[4:5], 0, s[8:9]
	v_add_co_u32_e64 v18, s[4:5], s77, v16
	global_load_dword v90, v[16:17], off
	s_nop 0
	v_addc_co_u32_e64 v19, s[4:5], 0, v17, s[4:5]
	v_add_co_u32_e64 v20, s[4:5], s87, v16
	s_nop 0
	v_addc_co_u32_e64 v21, s[4:5], 0, v17, s[4:5]
	v_add_co_u32_e64 v22, s[4:5], s76, v16
	s_add_u32 s8, s8, 0x30000
	s_nop 0
	v_addc_co_u32_e64 v23, s[4:5], 0, v17, s[4:5]
	s_mov_b32 s4, 0x18000
	s_nop 0
	v_add_co_u32_e64 v24, s[4:5], s4, v16
	s_addc_u32 s9, s9, 0
	s_nop 0
	v_addc_co_u32_e64 v25, s[4:5], 0, v17, s[4:5]
	s_mov_b32 s4, 0x1e000
	s_nop 0
	v_add_co_u32_e64 v26, s[4:5], s4, v16
	s_nop 0
	v_addc_co_u32_e64 v27, s[4:5], 0, v17, s[4:5]
	s_mov_b32 s4, 0x24000
	s_nop 0
	v_add_co_u32_e64 v28, s[4:5], s4, v16
	s_nop 0
	v_addc_co_u32_e64 v29, s[4:5], 0, v17, s[4:5]
	s_mov_b32 s4, 0x2a000
	s_nop 0
	v_add_co_u32_e64 v16, s[4:5], s4, v16
	s_nop 1
	v_addc_co_u32_e64 v17, s[4:5], 0, v17, s[4:5]
	global_load_dword v92, v[18:19], off
	global_load_dword v94, v[20:21], off
	global_load_dword v96, v[22:23], off
	global_load_dword v98, v[24:25], off
	global_load_dword v100, v[26:27], off
	global_load_dword v102, v[28:29], off
	global_load_dword v104, v[16:17], off
	v_mov_b32_e32 v15, s10
	ds_read_b128 v[16:19], v15
	ds_read_b128 v[20:23], v15 offset:16
	ds_read_b128 v[24:27], v15 offset:4096
	ds_read_b128 v[28:31], v15 offset:4112
	ds_read_b128 v[32:35], v15 offset:8192
	ds_read_b128 v[36:39], v15 offset:8208
	ds_read_b128 v[40:43], v15 offset:12288
	ds_read_b128 v[44:47], v15 offset:12304
	ds_read_b128 v[48:51], v15 offset:16384
	ds_read_b128 v[52:55], v15 offset:16400
	s_waitcnt lgkmcnt(9)
	v_mov_b32_e32 v72, v16
	s_waitcnt lgkmcnt(7)
	v_mov_b32_e32 v73, v24
	v_mov_b32_e32 v24, v17
	v_mov_b32_e32 v16, v18
	v_mov_b32_e32 v17, v26
	v_mov_b32_e32 v26, v19
	s_waitcnt lgkmcnt(5)
	v_mov_b32_e32 v18, v32
	s_waitcnt lgkmcnt(3)
	v_mov_b32_e32 v19, v40
	v_mov_b32_e32 v40, v33
	v_mov_b32_e32 v32, v34
	v_mov_b32_e32 v33, v42
	v_mov_b32_e32 v42, v35
	v_mov_b32_e32 v34, v20
	v_mov_b32_e32 v35, v28
	v_mov_b32_e32 v28, v21
	v_mov_b32_e32 v20, v22
	v_mov_b32_e32 v21, v30
	v_mov_b32_e32 v30, v23
	v_mov_b32_e32 v22, v36
	s_waitcnt lgkmcnt(2)
	v_mov_b32_e32 v23, v44
	v_mov_b32_e32 v44, v37
	v_mov_b32_e32 v36, v38
	v_mov_b32_e32 v37, v46
	v_mov_b32_e32 v46, v39
	s_waitcnt vmcnt(31)
	v_pk_fma_f32 v[6:7], v[106:107], v[72:73], v[6:7] op_sel_hi:[0,1,1]
	v_pk_fma_f32 v[12:13], v[106:107], v[18:19], v[12:13] op_sel_hi:[0,1,1]
	s_waitcnt lgkmcnt(1)
	v_fmac_f32_e32 v14, v106, v48
	s_waitcnt vmcnt(30)
	v_pk_fma_f32 v[6:7], v[108:109], v[24:25], v[6:7] op_sel_hi:[0,1,1]
	v_pk_fma_f32 v[12:13], v[108:109], v[40:41], v[12:13] op_sel_hi:[0,1,1]
	v_fmac_f32_e32 v14, v108, v49
	s_waitcnt vmcnt(29)
	v_pk_fma_f32 v[6:7], v[110:111], v[16:17], v[6:7] op_sel_hi:[0,1,1]
	v_pk_fma_f32 v[12:13], v[110:111], v[32:33], v[12:13] op_sel_hi:[0,1,1]
	v_fmac_f32_e32 v14, v110, v50
	s_waitcnt vmcnt(28)
	v_pk_fma_f32 v[6:7], v[112:113], v[26:27], v[6:7] op_sel_hi:[0,1,1]
	v_pk_fma_f32 v[12:13], v[112:113], v[42:43], v[12:13] op_sel_hi:[0,1,1]
	v_fmac_f32_e32 v14, v112, v51
	s_waitcnt vmcnt(27)
	v_pk_fma_f32 v[6:7], v[114:115], v[34:35], v[6:7] op_sel_hi:[0,1,1]
	v_pk_fma_f32 v[12:13], v[114:115], v[22:23], v[12:13] op_sel_hi:[0,1,1]
	s_waitcnt lgkmcnt(0)
	v_fmac_f32_e32 v14, v114, v52
	s_waitcnt vmcnt(26)
	v_pk_fma_f32 v[6:7], v[116:117], v[28:29], v[6:7] op_sel_hi:[0,1,1]
	v_pk_fma_f32 v[12:13], v[116:117], v[44:45], v[12:13] op_sel_hi:[0,1,1]
	v_fmac_f32_e32 v14, v116, v53
	s_waitcnt vmcnt(25)
	v_pk_fma_f32 v[6:7], v[118:119], v[20:21], v[6:7] op_sel_hi:[0,1,1]
	v_pk_fma_f32 v[12:13], v[118:119], v[36:37], v[12:13] op_sel_hi:[0,1,1]
	v_fmac_f32_e32 v14, v118, v54
	s_waitcnt vmcnt(24)
	v_pk_fma_f32 v[6:7], v[120:121], v[30:31], v[6:7] op_sel_hi:[0,1,1]
	v_pk_fma_f32 v[12:13], v[120:121], v[46:47], v[12:13] op_sel_hi:[0,1,1]
	v_fmac_f32_e32 v14, v120, v55
	s_add_i32 s10, s10, 32
	v_lshl_add_u64 v[16:17], v[4:5], 0, s[8:9]
	v_add_co_u32_e64 v18, s[4:5], s77, v16
	global_load_dword v106, v[16:17], off
	s_nop 0
	v_addc_co_u32_e64 v19, s[4:5], 0, v17, s[4:5]
	v_add_co_u32_e64 v20, s[4:5], s87, v16
	s_nop 0
	v_addc_co_u32_e64 v21, s[4:5], 0, v17, s[4:5]
	v_add_co_u32_e64 v22, s[4:5], s76, v16
	s_add_u32 s8, s8, 0x30000
	s_nop 0
	v_addc_co_u32_e64 v23, s[4:5], 0, v17, s[4:5]
	s_mov_b32 s4, 0x18000
	s_nop 0
	v_add_co_u32_e64 v24, s[4:5], s4, v16
	s_addc_u32 s9, s9, 0
	s_nop 0
	v_addc_co_u32_e64 v25, s[4:5], 0, v17, s[4:5]
	s_mov_b32 s4, 0x1e000
	s_nop 0
	v_add_co_u32_e64 v26, s[4:5], s4, v16
	s_nop 0
	v_addc_co_u32_e64 v27, s[4:5], 0, v17, s[4:5]
	s_mov_b32 s4, 0x24000
	s_nop 0
	v_add_co_u32_e64 v28, s[4:5], s4, v16
	s_nop 0
	v_addc_co_u32_e64 v29, s[4:5], 0, v17, s[4:5]
	s_mov_b32 s4, 0x2a000
	s_nop 0
	v_add_co_u32_e64 v16, s[4:5], s4, v16
	s_nop 1
	v_addc_co_u32_e64 v17, s[4:5], 0, v17, s[4:5]
	global_load_dword v108, v[18:19], off
	global_load_dword v110, v[20:21], off
	global_load_dword v112, v[22:23], off
	global_load_dword v114, v[24:25], off
	global_load_dword v116, v[26:27], off
	global_load_dword v118, v[28:29], off
	global_load_dword v120, v[16:17], off
	v_mov_b32_e32 v15, s10
	ds_read_b128 v[16:19], v15
	ds_read_b128 v[20:23], v15 offset:16
	ds_read_b128 v[24:27], v15 offset:4096
	ds_read_b128 v[28:31], v15 offset:4112
	ds_read_b128 v[32:35], v15 offset:8192
	ds_read_b128 v[36:39], v15 offset:8208
	ds_read_b128 v[40:43], v15 offset:12288
	ds_read_b128 v[44:47], v15 offset:12304
	ds_read_b128 v[48:51], v15 offset:16384
	ds_read_b128 v[52:55], v15 offset:16400
	s_waitcnt lgkmcnt(9)
; __global__ void __launch_bounds__(512) mega(Params p) {
;     ...
;             for (int it = bx; it < DEPTH * 96; it += G) {
;                 const int i = it / 96, nb = it % 96; const float* Wp = p.in[4] + (size_t)i * 1024 * 6144 + nb * 64 + lane;
;                 float a0 = 0.f, a1 = 0.f, a2 = 0.f, a3 = 0.f, a4 = 0.f;
; #pragma unroll 8
;                 for (int kk = 0; kk < 128; ++kk) { const int k = wave * 128 + kk; const float w = Wp[(size_t)k * 6144];
;                     a0 += sv[k] * w; a1 += sv[1024 + k] * w; a2 += sv[2048 + k] * w; a3 += sv[3072 + k] * w; a4 += sv[4096 + k] * w; }
	v_mov_b32_e32 v72, v16
	s_waitcnt lgkmcnt(7)
	v_mov_b32_e32 v73, v24
	v_mov_b32_e32 v24, v17
	v_mov_b32_e32 v16, v18
	v_mov_b32_e32 v17, v26
	v_mov_b32_e32 v26, v19
	s_waitcnt lgkmcnt(5)
	v_mov_b32_e32 v18, v32
	s_waitcnt lgkmcnt(3)
	v_mov_b32_e32 v19, v40
	v_mov_b32_e32 v40, v33
	v_mov_b32_e32 v32, v34
	v_mov_b32_e32 v33, v42
	v_mov_b32_e32 v42, v35
	v_mov_b32_e32 v34, v20
	v_mov_b32_e32 v35, v28
	v_mov_b32_e32 v28, v21
	v_mov_b32_e32 v20, v22
	v_mov_b32_e32 v21, v30
	v_mov_b32_e32 v30, v23
	v_mov_b32_e32 v22, v36
	s_waitcnt lgkmcnt(2)
	v_mov_b32_e32 v23, v44
	v_mov_b32_e32 v44, v37
	v_mov_b32_e32 v36, v38
	v_mov_b32_e32 v37, v46
	v_mov_b32_e32 v46, v39
	s_waitcnt vmcnt(31)
	v_pk_fma_f32 v[6:7], v[56:57], v[72:73], v[6:7] op_sel_hi:[0,1,1]
	v_pk_fma_f32 v[12:13], v[56:57], v[18:19], v[12:13] op_sel_hi:[0,1,1]
	s_waitcnt lgkmcnt(1)
	v_fmac_f32_e32 v14, v56, v48
	s_waitcnt vmcnt(30)
	v_pk_fma_f32 v[6:7], v[58:59], v[24:25], v[6:7] op_sel_hi:[0,1,1]
	v_pk_fma_f32 v[12:13], v[58:59], v[40:41], v[12:13] op_sel_hi:[0,1,1]
	v_fmac_f32_e32 v14, v58, v49
	s_waitcnt vmcnt(29)
	v_pk_fma_f32 v[6:7], v[60:61], v[16:17], v[6:7] op_sel_hi:[0,1,1]
	v_pk_fma_f32 v[12:13], v[60:61], v[32:33], v[12:13] op_sel_hi:[0,1,1]
	v_fmac_f32_e32 v14, v60, v50
	s_waitcnt vmcnt(28)
	v_pk_fma_f32 v[6:7], v[62:63], v[26:27], v[6:7] op_sel_hi:[0,1,1]
	v_pk_fma_f32 v[12:13], v[62:63], v[42:43], v[12:13] op_sel_hi:[0,1,1]
	v_fmac_f32_e32 v14, v62, v51
	s_waitcnt vmcnt(27)
	v_pk_fma_f32 v[6:7], v[64:65], v[34:35], v[6:7] op_sel_hi:[0,1,1]
	v_pk_fma_f32 v[12:13], v[64:65], v[22:23], v[12:13] op_sel_hi:[0,1,1]
	s_waitcnt lgkmcnt(0)
	v_fmac_f32_e32 v14, v64, v52
	s_waitcnt vmcnt(26)
	v_pk_fma_f32 v[6:7], v[66:67], v[28:29], v[6:7] op_sel_hi:[0,1,1]
	v_pk_fma_f32 v[12:13], v[66:67], v[44:45], v[12:13] op_sel_hi:[0,1,1]
	v_fmac_f32_e32 v14, v66, v53
	s_waitcnt vmcnt(25)
	v_pk_fma_f32 v[6:7], v[68:69], v[20:21], v[6:7] op_sel_hi:[0,1,1]
	v_pk_fma_f32 v[12:13], v[68:69], v[36:37], v[12:13] op_sel_hi:[0,1,1]
	v_fmac_f32_e32 v14, v68, v54
	s_waitcnt vmcnt(24)
	v_pk_fma_f32 v[6:7], v[70:71], v[30:31], v[6:7] op_sel_hi:[0,1,1]
	v_pk_fma_f32 v[12:13], v[70:71], v[46:47], v[12:13] op_sel_hi:[0,1,1]
	v_fmac_f32_e32 v14, v70, v55
	s_add_i32 s10, s10, 32
	v_mov_b32_e32 v15, s10
	ds_read_b128 v[16:19], v15
	ds_read_b128 v[20:23], v15 offset:16
	ds_read_b128 v[24:27], v15 offset:4096
	ds_read_b128 v[28:31], v15 offset:4112
	ds_read_b128 v[32:35], v15 offset:8192
	ds_read_b128 v[36:39], v15 offset:8208
	ds_read_b128 v[40:43], v15 offset:12288
	ds_read_b128 v[44:47], v15 offset:12304
	ds_read_b128 v[48:51], v15 offset:16384
	ds_read_b128 v[52:55], v15 offset:16400
	s_waitcnt lgkmcnt(9)
	v_mov_b32_e32 v72, v16
	s_waitcnt lgkmcnt(7)
	v_mov_b32_e32 v73, v24
	v_mov_b32_e32 v24, v17
	v_mov_b32_e32 v16, v18
	v_mov_b32_e32 v17, v26
	v_mov_b32_e32 v26, v19
	s_waitcnt lgkmcnt(5)
	v_mov_b32_e32 v18, v32
	s_waitcnt lgkmcnt(3)
	v_mov_b32_e32 v19, v40
	v_mov_b32_e32 v40, v33
	v_mov_b32_e32 v32, v34
	v_mov_b32_e32 v33, v42
	v_mov_b32_e32 v42, v35
	v_mov_b32_e32 v34, v20
	v_mov_b32_e32 v35, v28
	v_mov_b32_e32 v28, v21
	v_mov_b32_e32 v20, v22
	v_mov_b32_e32 v21, v30
	v_mov_b32_e32 v30, v23
	v_mov_b32_e32 v22, v36
	s_waitcnt lgkmcnt(2)
	v_mov_b32_e32 v23, v44
	v_mov_b32_e32 v44, v37
	v_mov_b32_e32 v36, v38
	v_mov_b32_e32 v37, v46
	v_mov_b32_e32 v46, v39
	s_waitcnt vmcnt(23)
	v_pk_fma_f32 v[6:7], v[74:75], v[72:73], v[6:7] op_sel_hi:[0,1,1]
	v_pk_fma_f32 v[12:13], v[74:75], v[18:19], v[12:13] op_sel_hi:[0,1,1]
	s_waitcnt lgkmcnt(1)
	v_fmac_f32_e32 v14, v74, v48
	s_waitcnt vmcnt(22)
	v_pk_fma_f32 v[6:7], v[76:77], v[24:25], v[6:7] op_sel_hi:[0,1,1]
	v_pk_fma_f32 v[12:13], v[76:77], v[40:41], v[12:13] op_sel_hi:[0,1,1]
	v_fmac_f32_e32 v14, v76, v49
	s_waitcnt vmcnt(21)
	v_pk_fma_f32 v[6:7], v[78:79], v[16:17], v[6:7] op_sel_hi:[0,1,1]
	v_pk_fma_f32 v[12:13], v[78:79], v[32:33], v[12:13] op_sel_hi:[0,1,1]
	v_fmac_f32_e32 v14, v78, v50
	s_waitcnt vmcnt(20)
	v_pk_fma_f32 v[6:7], v[80:81], v[26:27], v[6:7] op_sel_hi:[0,1,1]
	v_pk_fma_f32 v[12:13], v[80:81], v[42:43], v[12:13] op_sel_hi:[0,1,1]
	v_fmac_f32_e32 v14, v80, v51
	s_waitcnt vmcnt(19)
	v_pk_fma_f32 v[6:7], v[82:83], v[34:35], v[6:7] op_sel_hi:[0,1,1]
	v_pk_fma_f32 v[12:13], v[82:83], v[22:23], v[12:13] op_sel_hi:[0,1,1]
	s_waitcnt lgkmcnt(0)
	v_fmac_f32_e32 v14, v82, v52
	s_waitcnt vmcnt(18)
	v_pk_fma_f32 v[6:7], v[84:85], v[28:29], v[6:7] op_sel_hi:[0,1,1]
	v_pk_fma_f32 v[12:13], v[84:85], v[44:45], v[12:13] op_sel_hi:[0,1,1]
	v_fmac_f32_e32 v14, v84, v53
	s_waitcnt vmcnt(17)
	v_pk_fma_f32 v[6:7], v[86:87], v[20:21], v[6:7] op_sel_hi:[0,1,1]
	v_pk_fma_f32 v[12:13], v[86:87], v[36:37], v[12:13] op_sel_hi:[0,1,1]
	v_fmac_f32_e32 v14, v86, v54
	s_waitcnt vmcnt(16)
	v_pk_fma_f32 v[6:7], v[88:89], v[30:31], v[6:7] op_sel_hi:[0,1,1]
	v_pk_fma_f32 v[12:13], v[88:89], v[46:47], v[12:13] op_sel_hi:[0,1,1]
	v_fmac_f32_e32 v14, v88, v55
	s_add_i32 s10, s10, 32
	v_mov_b32_e32 v15, s10
	ds_read_b128 v[16:19], v15
	ds_read_b128 v[20:23], v15 offset:16
	ds_read_b128 v[24:27], v15 offset:4096
	ds_read_b128 v[28:31], v15 offset:4112
	ds_read_b128 v[32:35], v15 offset:8192
	ds_read_b128 v[36:39], v15 offset:8208
	ds_read_b128 v[40:43], v15 offset:12288
	ds_read_b128 v[44:47], v15 offset:12304
	ds_read_b128 v[48:51], v15 offset:16384
	ds_read_b128 v[52:55], v15 offset:16400
	s_waitcnt lgkmcnt(9)
	v_mov_b32_e32 v72, v16
	s_waitcnt lgkmcnt(7)
	v_mov_b32_e32 v73, v24
	v_mov_b32_e32 v24, v17
	v_mov_b32_e32 v16, v18
	v_mov_b32_e32 v17, v26
	v_mov_b32_e32 v26, v19
	s_waitcnt lgkmcnt(5)
	v_mov_b32_e32 v18, v32
	s_waitcnt lgkmcnt(3)
; __global__ void __launch_bounds__(512) mega(Params p) {
;     ...
;                 for (int kk = 0; kk < 128; ++kk) { const int k = wave * 128 + kk; const float w = Wp[(size_t)k * 6144];
;                     a0 += sv[k] * w; a1 += sv[1024 + k] * w; a2 += sv[2048 + k] * w; a3 += sv[3072 + k] * w; a4 += sv[4096 + k] * w; }
;                 red[(wave * 5 + 0) * 64 + lane] = a0; red[(wave * 5 + 1) * 64 + lane] = a1; red[(wave * 5 + 2) * 64 + lane] = a2; red[(wave * 5 + 3) * 64 + lane] = a3; red[(wave * 5 + 4) * 64 + lane] = a4;
;                 __syncthreads();
;                 if (tid < 320) { const int j = tid >> 6, l = tid & 63; float s = 0.f;
; #pragma unroll
;                     for (int w = 0; w < 8; ++w) s += red[(w * 5 + j) * 64 + l];
;                     mod[((size_t)i * 5 + j) * 6144 + nb * 64 + l] = s + p.in[5][(size_t)i * 6144 + nb * 64 + l]; }
	v_mov_b32_e32 v19, v40
	v_mov_b32_e32 v40, v33
	v_mov_b32_e32 v32, v34
	v_mov_b32_e32 v33, v42
	v_mov_b32_e32 v42, v35
	v_mov_b32_e32 v34, v20
	v_mov_b32_e32 v35, v28
	v_mov_b32_e32 v28, v21
	v_mov_b32_e32 v20, v22
	v_mov_b32_e32 v21, v30
	v_mov_b32_e32 v30, v23
	v_mov_b32_e32 v22, v36
	s_waitcnt lgkmcnt(2)
	v_mov_b32_e32 v23, v44
	v_mov_b32_e32 v44, v37
	v_mov_b32_e32 v36, v38
	v_mov_b32_e32 v37, v46
	v_mov_b32_e32 v46, v39
	s_waitcnt vmcnt(15)
	v_pk_fma_f32 v[6:7], v[90:91], v[72:73], v[6:7] op_sel_hi:[0,1,1]
	v_pk_fma_f32 v[12:13], v[90:91], v[18:19], v[12:13] op_sel_hi:[0,1,1]
	s_waitcnt lgkmcnt(1)
	v_fmac_f32_e32 v14, v90, v48
	s_waitcnt vmcnt(14)
	v_pk_fma_f32 v[6:7], v[92:93], v[24:25], v[6:7] op_sel_hi:[0,1,1]
	v_pk_fma_f32 v[12:13], v[92:93], v[40:41], v[12:13] op_sel_hi:[0,1,1]
	v_fmac_f32_e32 v14, v92, v49
	s_waitcnt vmcnt(13)
	v_pk_fma_f32 v[6:7], v[94:95], v[16:17], v[6:7] op_sel_hi:[0,1,1]
	v_pk_fma_f32 v[12:13], v[94:95], v[32:33], v[12:13] op_sel_hi:[0,1,1]
	v_fmac_f32_e32 v14, v94, v50
	s_waitcnt vmcnt(12)
	v_pk_fma_f32 v[6:7], v[96:97], v[26:27], v[6:7] op_sel_hi:[0,1,1]
	v_pk_fma_f32 v[12:13], v[96:97], v[42:43], v[12:13] op_sel_hi:[0,1,1]
	v_fmac_f32_e32 v14, v96, v51
	s_waitcnt vmcnt(11)
	v_pk_fma_f32 v[6:7], v[98:99], v[34:35], v[6:7] op_sel_hi:[0,1,1]
	v_pk_fma_f32 v[12:13], v[98:99], v[22:23], v[12:13] op_sel_hi:[0,1,1]
	s_waitcnt lgkmcnt(0)
	v_fmac_f32_e32 v14, v98, v52
	s_waitcnt vmcnt(10)
	v_pk_fma_f32 v[6:7], v[100:101], v[28:29], v[6:7] op_sel_hi:[0,1,1]
	v_pk_fma_f32 v[12:13], v[100:101], v[44:45], v[12:13] op_sel_hi:[0,1,1]
	v_fmac_f32_e32 v14, v100, v53
	s_waitcnt vmcnt(9)
	v_pk_fma_f32 v[6:7], v[102:103], v[20:21], v[6:7] op_sel_hi:[0,1,1]
	v_pk_fma_f32 v[12:13], v[102:103], v[36:37], v[12:13] op_sel_hi:[0,1,1]
	v_fmac_f32_e32 v14, v102, v54
	s_waitcnt vmcnt(8)
	v_pk_fma_f32 v[6:7], v[104:105], v[30:31], v[6:7] op_sel_hi:[0,1,1]
	v_pk_fma_f32 v[12:13], v[104:105], v[46:47], v[12:13] op_sel_hi:[0,1,1]
	v_fmac_f32_e32 v14, v104, v55
	s_add_i32 s10, s10, 32
	v_mov_b32_e32 v15, s10
	ds_read_b128 v[16:19], v15
	ds_read_b128 v[20:23], v15 offset:16
	ds_read_b128 v[24:27], v15 offset:4096
	ds_read_b128 v[28:31], v15 offset:4112
	ds_read_b128 v[32:35], v15 offset:8192
	ds_read_b128 v[36:39], v15 offset:8208
	ds_read_b128 v[40:43], v15 offset:12288
	ds_read_b128 v[44:47], v15 offset:12304
	ds_read_b128 v[48:51], v15 offset:16384
	ds_read_b128 v[52:55], v15 offset:16400
	s_waitcnt lgkmcnt(9)
	v_mov_b32_e32 v72, v16
	s_waitcnt lgkmcnt(7)
	v_mov_b32_e32 v73, v24
	v_mov_b32_e32 v24, v17
	v_mov_b32_e32 v16, v18
	v_mov_b32_e32 v17, v26
	v_mov_b32_e32 v26, v19
	s_waitcnt lgkmcnt(5)
	v_mov_b32_e32 v18, v32
	s_waitcnt lgkmcnt(3)
	v_mov_b32_e32 v19, v40
	v_mov_b32_e32 v40, v33
	v_mov_b32_e32 v32, v34
	v_mov_b32_e32 v33, v42
	v_mov_b32_e32 v42, v35
	v_mov_b32_e32 v34, v20
	v_mov_b32_e32 v35, v28
	v_mov_b32_e32 v28, v21
	v_mov_b32_e32 v20, v22
	v_mov_b32_e32 v21, v30
	v_mov_b32_e32 v30, v23
	v_mov_b32_e32 v22, v36
	s_waitcnt lgkmcnt(2)
	v_mov_b32_e32 v23, v44
	v_mov_b32_e32 v44, v37
	v_mov_b32_e32 v36, v38
	v_mov_b32_e32 v37, v46
	v_mov_b32_e32 v46, v39
	s_waitcnt vmcnt(7)
	v_pk_fma_f32 v[6:7], v[106:107], v[72:73], v[6:7] op_sel_hi:[0,1,1]
	v_pk_fma_f32 v[12:13], v[106:107], v[18:19], v[12:13] op_sel_hi:[0,1,1]
	s_waitcnt lgkmcnt(1)
	v_fmac_f32_e32 v14, v106, v48
	s_waitcnt vmcnt(6)
	v_pk_fma_f32 v[6:7], v[108:109], v[24:25], v[6:7] op_sel_hi:[0,1,1]
	v_pk_fma_f32 v[12:13], v[108:109], v[40:41], v[12:13] op_sel_hi:[0,1,1]
	v_fmac_f32_e32 v14, v108, v49
	s_waitcnt vmcnt(5)
	v_pk_fma_f32 v[6:7], v[110:111], v[16:17], v[6:7] op_sel_hi:[0,1,1]
	v_pk_fma_f32 v[12:13], v[110:111], v[32:33], v[12:13] op_sel_hi:[0,1,1]
	v_fmac_f32_e32 v14, v110, v50
	s_waitcnt vmcnt(4)
	v_pk_fma_f32 v[6:7], v[112:113], v[26:27], v[6:7] op_sel_hi:[0,1,1]
	v_pk_fma_f32 v[12:13], v[112:113], v[42:43], v[12:13] op_sel_hi:[0,1,1]
	v_fmac_f32_e32 v14, v112, v51
	s_waitcnt vmcnt(3)
	v_pk_fma_f32 v[6:7], v[114:115], v[34:35], v[6:7] op_sel_hi:[0,1,1]
	v_pk_fma_f32 v[12:13], v[114:115], v[22:23], v[12:13] op_sel_hi:[0,1,1]
	s_waitcnt lgkmcnt(0)
	v_fmac_f32_e32 v14, v114, v52
	s_waitcnt vmcnt(2)
	v_pk_fma_f32 v[6:7], v[116:117], v[28:29], v[6:7] op_sel_hi:[0,1,1]
	v_pk_fma_f32 v[12:13], v[116:117], v[44:45], v[12:13] op_sel_hi:[0,1,1]
	v_fmac_f32_e32 v14, v116, v53
	s_waitcnt vmcnt(1)
	v_pk_fma_f32 v[6:7], v[118:119], v[20:21], v[6:7] op_sel_hi:[0,1,1]
	v_pk_fma_f32 v[12:13], v[118:119], v[36:37], v[12:13] op_sel_hi:[0,1,1]
	v_fmac_f32_e32 v14, v118, v54
	s_waitcnt vmcnt(0)
	v_pk_fma_f32 v[6:7], v[120:121], v[30:31], v[6:7] op_sel_hi:[0,1,1]
	v_pk_fma_f32 v[12:13], v[120:121], v[46:47], v[12:13] op_sel_hi:[0,1,1]
	v_fmac_f32_e32 v14, v120, v55
	s_add_i32 s10, s10, 32
	ds_write2st64_b32 v9, v6, v7 offset0:80 offset1:81
	ds_write2st64_b32 v9, v12, v13 offset0:82 offset1:83
	ds_write_b32 v9, v14 offset:21504
	s_waitcnt lgkmcnt(0)
	s_barrier
	s_and_saveexec_b64 s[4:5], vcc
	s_cbranch_execz .LBB0_629
	s_load_dwordx2 s[8:9], s[90:91], 0x28
	s_mul_i32 s11, s3, 0x6000
	s_mul_hi_i32 s10, s3, 0x6000
	v_mov_b64_e32 v[18:19], s[30:31]
	s_waitcnt lgkmcnt(0)
	s_add_u32 s8, s8, s11
	s_addc_u32 s9, s9, s10
	s_add_u32 s8, s8, s6
	s_addc_u32 s9, s9, s7
	global_load_dword v20, v208, s[8:9]
	ds_read2st64_b32 v[4:5], v11 offset0:80 offset1:85
	ds_read2st64_b32 v[6:7], v11 offset0:90 offset1:95
	ds_read2st64_b32 v[12:13], v11 offset0:100 offset1:105
	ds_read2st64_b32 v[14:15], v11 offset0:110 offset1:115
	v_mad_i64_i32 v[16:17], s[8:9], s3, 5, v[0:1]
	s_waitcnt lgkmcnt(3)
	v_add_f32_e32 v4, 0, v4
	v_add_f32_e32 v4, v4, v5
	s_waitcnt lgkmcnt(2)
	v_add_f32_e32 v4, v4, v6
	v_add_f32_e32 v4, v4, v7
	s_waitcnt lgkmcnt(1)
	v_add_f32_e32 v4, v4, v12
	v_mad_u64_u32 v[18:19], s[8:9], v16, s77, v[18:19]
	v_add_f32_e32 v4, v4, v13
	v_mad_i32_i24 v19, v17, s77, v19
	s_waitcnt lgkmcnt(0)
	v_add_f32_e32 v4, v4, v14
	v_lshl_add_u64 v[16:17], v[18:19], 0, s[6:7]
	v_add_f32_e32 v4, v4, v15
	s_waitcnt vmcnt(0)
	v_add_f32_e32 v6, v4, v20
	v_lshl_add_u64 v[4:5], v[16:17], 0, v[208:209]
	global_store_dword v[4:5], v6, off
	s_branch .LBB0_629
